# attn_d: next-tile staging loads issued inside X right after the ds_writes; q-norm gains read from an LDS copy
# baseline (speedup 1.0000x reference)
; template <int DQK, int KA8, int DV, bool BIAS, bool JOINT>
; DI void attn_core(LAS unsigned char* lds, const bf16_t* Qrow, const bf16_t* KpA, int ldkA, const bf16_t* KpB, int ldkB, const bf16_t* Vp, int ldv,
;                   int qb, int wid, int lane, const float* qng  , f32x16 (&O)[DV / 32]) {
;     ...
;     const int tid = otid(), l32 = lane & 31, hh = lane >> 5, i16 = lane & 15, tq = i16 >> 2, tp = i16 & 3, blk = (lane >> 4) & 1;
;     const int q0w = qb * 256 + wid * 32, nkt = 4 * qb + 4, myc = q0w >> 6;
;     bf16x8 qf[DQK / 16];
; #pragma unroll
;     for (int s = 0; s < DQK / 16; ++s) qf[s] = *(const bf16x8*)(Qrow + 16 * s + 8 * hh);
;     if constexpr (DQK == 192) {
;         if (qng) {
;             float ssn = 0.f, ssr = 0.f;
; #pragma unroll
;             for (int s = 0; s < 12; ++s) { float f[8]; unpack8(__builtin_bit_cast(u32x4, qf[s]), f); float t = 0.f;
; #pragma unroll
;                 for (int e = 0; e < 8; ++e) t += f[e] * f[e];
;                 if (s < 8) ssn += t; else ssr += t; }
;             ssn += __shfl_xor(ssn, 32); ssr += __shfl_xor(ssr, 32);
;             const float qs = 0.07216878364870322f * LOG2E, scn = rsqrtf(ssn * (1.f / 128.f) + EPS) * qs, scr = rsqrtf(ssr * (1.f / 64.f) + EPS) * qs;
; #pragma unroll
;             for (int s = 0; s < 8; ++s) { float f[8]; unpack8(__builtin_bit_cast(u32x4, qf[s]), f);
;                 const f32x4 g0 = *(const f32x4*)(qng + 16 * s + 8 * hh), g1 = *(const f32x4*)(qng + 16 * s + 8 * hh + 4);
; #pragma unroll
;                 for (int e = 0; e < 4; ++e) { f[e] *= scn * g0[e]; f[4 + e] *= scn * g1[e]; }
;                 qf[s] = __builtin_bit_cast(bf16x8, pack8(f)); }
;             const float posr = (float)(qb * 256 + wid * 32 + l32) * 0.15915494309189535f;
; #pragma unroll
;             for (int s = 8; s < 10; ++s) { float f1[8], f2[8]; unpack8(__builtin_bit_cast(u32x4, qf[s]), f1); unpack8(__builtin_bit_cast(u32x4, qf[s + 2]), f2);
; #pragma unroll
;                 for (int e = 0; e < 8; ++e) { const int i = 16 * (s - 8) + 8 * hh + e;
;                     const float a1 = f1[e] * scr * qng[128 + i], a2 = f2[e] * scr * qng[160 + i];
;                     float rev = posr * __builtin_amdgcn_exp2f(-(float)i * 0.41524101186092029f); rev -= floorf(rev);
;                     const float sn = __builtin_amdgcn_sinf(rev), cs = __builtin_amdgcn_cosf(rev);
.LBB0_1556:
	s_or_b64 exec, exec, s[6:7]
	s_and_b64 vcc, exec, s[4:5]
	s_waitcnt lgkmcnt(0)
	s_barrier
	s_cbranch_vccnz .LBB0_1625
	s_load_dwordx2 s[6:7], s[0:1], 0xf0
	s_load_dwordx2 s[12:13], s[0:1], 0xd8
	v_and_b32_e32 v228, 63, v181
	v_and_b32_e32 v226, 31, v228
	v_lshrrev_b32_e32 v227, 5, v228
	v_mul_u32_u24_e32 v214, 400, v226
	v_lshl_add_u32 v214, v227, 4, v214
	v_bfe_u32 v235, v228, 2, 2
	v_lshl_add_u32 v235, v227, 2, v235
	v_mul_u32_u24_e32 v215, 320, v235
	v_and_b32_e32 v235, 3, v228
	v_lshl_add_u32 v215, v235, 3, v215
	v_bfe_u32 v235, v228, 4, 1
	v_lshl_add_u32 v215, v235, 5, v215
	v_lshrrev_b32_e32 v235, 4, v181
	v_and_b32_e32 v236, 15, v181
	v_mul_u32_u24_e32 v216, 400, v235
	v_lshl_add_u32 v216, v236, 4, v216
	v_mul_u32_u24_e32 v218, 320, v235
	v_lshl_add_u32 v218, v236, 4, v218
	v_mul_u32_u24_e32 v219, 14336, v235
	v_lshl_add_u32 v219, v236, 4, v219
	v_add_u32_e32 v220, 0x70000, v219
	v_mov_b32_e32 v222, v219
	v_mov_b32_e32 v223, v220
	v_lshrrev_b32_e32 v235, 3, v181
	v_and_b32_e32 v236, 7, v181
	v_mul_u32_u24_e32 v217, 400, v235
	v_lshl_add_u32 v217, v236, 4, v217
	v_add_u32_e32 v217, 256, v217
	v_add_u32_e32 v253, 66560, v216
	v_add_u32_e32 v254, 66560, v217
	v_add_u32_e32 v252, 66560, v214
	v_mul_u32_u24_e32 v221, 2176, v235
	v_lshl_add_u32 v221, v236, 4, v221
	v_mul_u32_u24_e32 v237, 14336, v226
	v_lshl_add_u32 v237, v227, 4, v237
	v_lshlrev_b32_e32 v238, 12, v226
	v_lshl_add_u32 v238, v227, 3, v238
	v_lshlrev_b32_e32 v239, 5, v227
	v_lshrrev_b32_e32 v235, 6, v181
	s_nop 0
	v_readfirstlane_b32 s26, v235
	s_waitcnt lgkmcnt(0)
	v_cmp_gt_u32_e32 vcc, 192, v181
	s_and_saveexec_b64 s[66:67], vcc
	s_cbranch_execz .Lad_gnskip
	v_lshlrev_b32_e32 v229, 2, v181
	global_load_dword v230, v229, s[12:13]
	v_add_u32_e32 v229, 92160, v229
	s_waitcnt vmcnt(0)
	ds_write_b32 v229, v230
	s_waitcnt lgkmcnt(0)
.Lad_gnskip:
	s_or_b64 exec, exec, s[66:67]
	v_add_u32_e32 v239, 92160, v239
	s_add_u32 s8, s6, 0xbf00000
	s_addc_u32 s9, s7, 0
	s_add_u32 s10, s6, 0x7f00000
	s_addc_u32 s11, s7, 0
	s_mov_b32 s14, s2

; template <int DQK, int KA8, int DV, bool BIAS, bool JOINT>
; DI void attn_core(LAS unsigned char* lds, const bf16_t* Qrow, const bf16_t* KpA, int ldkA, const bf16_t* KpB, int ldkB, const bf16_t* Vp, int ldv,
;                   int qb, int wid, int lane, const float* qng  , f32x16 (&O)[DV / 32]) {
;     ...
;     const int q0w = qb * 256 + wid * 32, nkt = 4 * qb + 4, myc = q0w >> 6;
;     bf16x8 qf[DQK / 16];
; #pragma unroll
;     for (int s = 0; s < DQK / 16; ++s) qf[s] = *(const bf16x8*)(Qrow + 16 * s + 8 * hh);
;     if constexpr (DQK == 192) {
;         if (qng) {
;             float ssn = 0.f, ssr = 0.f;
; #pragma unroll
;             for (int s = 0; s < 12; ++s) { float f[8]; unpack8(__builtin_bit_cast(u32x4, qf[s]), f); float t = 0.f;
; #pragma unroll
;                 for (int e = 0; e < 8; ++e) t += f[e] * f[e];
;                 if (s < 8) ssn += t; else ssr += t; }
;             ssn += __shfl_xor(ssn, 32); ssr += __shfl_xor(ssr, 32);
;             const float qs = 0.07216878364870322f * LOG2E, scn = rsqrtf(ssn * (1.f / 128.f) + EPS) * qs, scr = rsqrtf(ssr * (1.f / 64.f) + EPS) * qs;
; #pragma unroll
;             for (int s = 0; s < 8; ++s) { float f[8]; unpack8(__builtin_bit_cast(u32x4, qf[s]), f);
;                 const f32x4 g0 = *(const f32x4*)(qng + 16 * s + 8 * hh), g1 = *(const f32x4*)(qng + 16 * s + 8 * hh + 4);
; #pragma unroll
;                 for (int e = 0; e < 4; ++e) { f[e] *= scn * g0[e]; f[4 + e] *= scn * g1[e]; }
;                 qf[s] = __builtin_bit_cast(bf16x8, pack8(f)); }
;             const float posr = (float)(qb * 256 + wid * 32 + l32) * 0.15915494309189535f;
; #pragma unroll
;             for (int s = 8; s < 10; ++s) { float f1[8], f2[8]; unpack8(__builtin_bit_cast(u32x4, qf[s]), f1); unpack8(__builtin_bit_cast(u32x4, qf[s + 2]), f2);
; #pragma unroll
;                 for (int e = 0; e < 8; ++e) { const int i = 16 * (s - 8) + 8 * hh + e;
;                     const float a1 = f1[e] * scr * qng[128 + i], a2 = f2[e] * scr * qng[160 + i];
;                     float rev = posr * __builtin_amdgcn_exp2f(-(float)i * 0.41524101186092029f); rev -= floorf(rev);
;                     const float sn = __builtin_amdgcn_sinf(rev), cs = __builtin_amdgcn_cosf(rev);
;                     f1[e] = a1 * cs - a2 * sn; f2[e] = a2 * cs + a1 * sn; }
.Lad_half:
	s_sub_i32 s58, 15, s29
	s_cmp_eq_u32 s15, 0
	s_cselect_b32 s16, s29, s58
	s_lshl_b32 s17, s16, 2
	s_add_i32 s17, s17, 4
	s_lshl_b32 s43, s16, 8
	s_lshl_b32 s58, s26, 5
	s_add_i32 s43, s43, s58
	s_lshr_b32 s25, s43, 6
	s_lshl_b32 s58, s28, 12
	s_add_i32 s59, s58, s43
	s_mul_i32 s60, s59, 14336
	s_mul_hi_u32 s61, s59, 14336
	s_mul_i32 s42, s27, 384
	s_add_u32 s46, s8, s60
	s_addc_u32 s47, s9, s61
	s_add_u32 s46, s46, s42
	s_addc_u32 s47, s47, 0
	s_mul_i32 s60, s58, 14336
	s_mul_hi_u32 s61, s58, 14336
	s_lshl_b32 s42, s27, 9
	s_add_u32 s48, s8, s60
	s_addc_u32 s49, s9, s61
	s_add_u32 s48, s48, s42
	s_addc_u32 s49, s49, 0
	s_add_u32 s48, s48, 0x1800
	s_addc_u32 s49, s49, 0
	s_add_u32 s50, s48, 0x100
	s_addc_u32 s51, s49, 0
	s_mul_i32 s60, s58, 2176
	s_mul_hi_u32 s61, s58, 2176
	s_add_u32 s52, s6, s60
	s_addc_u32 s53, s7, s61
	s_add_u32 s52, s52, 0x800
	s_addc_u32 s53, s53, 0
	s_mov_b32 s60, s59
	s_mov_b32 s61, 0
	s_lshl_b64 s[60:61], s[60:61], 12
	s_lshl_b32 s42, s27, 8
	s_add_u32 s54, s10, s60
	s_addc_u32 s55, s11, s61
	s_add_u32 s54, s54, s42
	s_addc_u32 s55, s55, 0
	v_add_u32_e32 v229, s43, v226
	v_cvt_f32_u32_e32 v229, v229
	v_mul_f32_e32 v240, 0x3e22f983, v229
	s_barrier
	s_mov_b64 s[30:31], s[48:49]
	s_mov_b64 s[36:37], s[52:53]
	s_mov_b64 s[34:35], s[50:51]
	global_load_dwordx4 v[160:163], v219, s[30:31]
	global_load_dwordx4 v[164:167], v220, s[30:31]
	global_load_dwordx4 v[168:171], v221, s[36:37]
	global_load_dwordx4 v[112:115], v237, s[46:47] offset:0
	global_load_dwordx4 v[116:119], v237, s[46:47] offset:32
	global_load_dwordx4 v[120:123], v237, s[46:47] offset:64
	global_load_dwordx4 v[124:127], v237, s[46:47] offset:96
	global_load_dwordx4 v[128:131], v237, s[46:47] offset:128
	global_load_dwordx4 v[132:135], v237, s[46:47] offset:160
	global_load_dwordx4 v[136:139], v237, s[46:47] offset:192
	global_load_dwordx4 v[140:143], v237, s[46:47] offset:224
	global_load_dwordx4 v[144:147], v237, s[46:47] offset:256
	global_load_dwordx4 v[148:151], v237, s[46:47] offset:288
	global_load_dwordx4 v[152:155], v237, s[46:47] offset:320
	global_load_dwordx4 v[156:159], v237, s[46:47] offset:352
	s_add_u32 s30, s30, 0xe0000
	s_addc_u32 s31, s31, 0
	s_add_u32 s36, s36, 0x22000
	s_addc_u32 s37, s37, 0
	v_mov_b32_e32 v0, 0
	v_mov_b32_e32 v1, 0
	v_mov_b32_e32 v2, 0
	v_mov_b32_e32 v3, 0
	v_mov_b32_e32 v4, 0
	v_mov_b32_e32 v5, 0
	v_mov_b32_e32 v6, 0
	v_mov_b32_e32 v7, 0
	v_mov_b32_e32 v8, 0
	v_mov_b32_e32 v9, 0
	v_mov_b32_e32 v10, 0
	v_mov_b32_e32 v11, 0
	v_mov_b32_e32 v12, 0
	v_mov_b32_e32 v13, 0
	v_mov_b32_e32 v14, 0
	v_mov_b32_e32 v15, 0
	v_mov_b32_e32 v16, 0
	v_mov_b32_e32 v17, 0
	v_mov_b32_e32 v18, 0
	v_mov_b32_e32 v19, 0
	v_mov_b32_e32 v20, 0
	v_mov_b32_e32 v21, 0
	v_mov_b32_e32 v22, 0
	v_mov_b32_e32 v23, 0
	v_mov_b32_e32 v24, 0
	v_mov_b32_e32 v25, 0
	v_mov_b32_e32 v26, 0
	v_mov_b32_e32 v27, 0
	v_mov_b32_e32 v28, 0
	v_mov_b32_e32 v29, 0
	v_mov_b32_e32 v30, 0
	v_mov_b32_e32 v31, 0
	v_mov_b32_e32 v32, 0
	v_mov_b32_e32 v33, 0
	v_mov_b32_e32 v34, 0
	v_mov_b32_e32 v35, 0
	v_mov_b32_e32 v36, 0
	v_mov_b32_e32 v37, 0
	v_mov_b32_e32 v38, 0
	v_mov_b32_e32 v39, 0
	v_mov_b32_e32 v40, 0
	v_mov_b32_e32 v41, 0
	v_mov_b32_e32 v42, 0
	v_mov_b32_e32 v43, 0
	v_mov_b32_e32 v44, 0
	v_mov_b32_e32 v45, 0
	v_mov_b32_e32 v46, 0
	v_mov_b32_e32 v47, 0
	v_mov_b32_e32 v48, 0
	v_mov_b32_e32 v49, 0
	v_mov_b32_e32 v50, 0
	v_mov_b32_e32 v51, 0
	v_mov_b32_e32 v52, 0
	v_mov_b32_e32 v53, 0
	v_mov_b32_e32 v54, 0
	v_mov_b32_e32 v55, 0
	v_mov_b32_e32 v56, 0
	v_mov_b32_e32 v57, 0
	v_mov_b32_e32 v58, 0
	v_mov_b32_e32 v59, 0
	v_mov_b32_e32 v60, 0
	v_mov_b32_e32 v61, 0
	v_mov_b32_e32 v62, 0
	v_mov_b32_e32 v63, 0
	v_mov_b32_e32 v224, 0
	v_mov_b32_e32 v225, 0
	s_mov_b32 s40, 0
	s_waitcnt vmcnt(12)
	ds_write_b128 v216, v[160:163] offset:40960
	ds_write_b128 v216, v[164:167] offset:53760
	ds_write_b128 v217, v[168:171] offset:40960
	s_waitcnt lgkmcnt(0)
	global_load_dwordx4 v[160:163], v219, s[30:31]
	global_load_dwordx4 v[164:167], v220, s[30:31]
	global_load_dwordx4 v[168:171], v221, s[36:37]
	global_load_dwordx4 v[172:175], v222, s[34:35]
	global_load_dwordx4 v[176:179], v223, s[34:35]
	s_add_u32 s30, s30, 0xe0000
	s_addc_u32 s31, s31, 0
	s_add_u32 s36, s36, 0x22000
	s_addc_u32 s37, s37, 0
	s_add_u32 s34, s34, 0xe0000
	s_addc_u32 s35, s35, 0
	s_waitcnt vmcnt(5)
; template <int DQK, int KA8, int DV, bool BIAS, bool JOINT>
; DI void attn_core(LAS unsigned char* lds, const bf16_t* Qrow, const bf16_t* KpA, int ldkA, const bf16_t* KpB, int ldkB, const bf16_t* Vp, int ldv,
;                   int qb, int wid, int lane, const float* qng  , f32x16 (&O)[DV / 32]) {
;     ...
;             float ssn = 0.f, ssr = 0.f;
; #pragma unroll
;             for (int s = 0; s < 12; ++s) { float f[8]; unpack8(__builtin_bit_cast(u32x4, qf[s]), f); float t = 0.f;
; #pragma unroll
;                 for (int e = 0; e < 8; ++e) t += f[e] * f[e];
;                 if (s < 8) ssn += t; else ssr += t; }
	v_lshlrev_b32_e32 v229, 16, v112
	v_and_b32_e32 v230, 0xffff0000, v112
	v_mul_f32_e32 v232, v229, v229
	v_fmac_f32_e32 v232, v230, v230
	v_lshlrev_b32_e32 v229, 16, v113
	v_and_b32_e32 v230, 0xffff0000, v113
	v_fmac_f32_e32 v232, v229, v229
	v_fmac_f32_e32 v232, v230, v230
	v_lshlrev_b32_e32 v229, 16, v114
	v_and_b32_e32 v230, 0xffff0000, v114
	v_fmac_f32_e32 v232, v229, v229
	v_fmac_f32_e32 v232, v230, v230
	v_lshlrev_b32_e32 v229, 16, v115
	v_and_b32_e32 v230, 0xffff0000, v115
	v_fmac_f32_e32 v232, v229, v229
	v_fmac_f32_e32 v232, v230, v230
	v_lshlrev_b32_e32 v229, 16, v116
	v_and_b32_e32 v230, 0xffff0000, v116
	v_fmac_f32_e32 v232, v229, v229
	v_fmac_f32_e32 v232, v230, v230
	v_lshlrev_b32_e32 v229, 16, v117
	v_and_b32_e32 v230, 0xffff0000, v117
	v_fmac_f32_e32 v232, v229, v229
	v_fmac_f32_e32 v232, v230, v230
	v_lshlrev_b32_e32 v229, 16, v118
	v_and_b32_e32 v230, 0xffff0000, v118
	v_fmac_f32_e32 v232, v229, v229
	v_fmac_f32_e32 v232, v230, v230
	v_lshlrev_b32_e32 v229, 16, v119
	v_and_b32_e32 v230, 0xffff0000, v119
	v_fmac_f32_e32 v232, v229, v229
	v_fmac_f32_e32 v232, v230, v230
	v_lshlrev_b32_e32 v229, 16, v120
	v_and_b32_e32 v230, 0xffff0000, v120
	v_fmac_f32_e32 v232, v229, v229
	v_fmac_f32_e32 v232, v230, v230
	v_lshlrev_b32_e32 v229, 16, v121
	v_and_b32_e32 v230, 0xffff0000, v121
	v_fmac_f32_e32 v232, v229, v229
	v_fmac_f32_e32 v232, v230, v230
	v_lshlrev_b32_e32 v229, 16, v122
	v_and_b32_e32 v230, 0xffff0000, v122
	v_fmac_f32_e32 v232, v229, v229
	v_fmac_f32_e32 v232, v230, v230
	v_lshlrev_b32_e32 v229, 16, v123
	v_and_b32_e32 v230, 0xffff0000, v123
	v_fmac_f32_e32 v232, v229, v229
	v_fmac_f32_e32 v232, v230, v230
	v_lshlrev_b32_e32 v229, 16, v124
	v_and_b32_e32 v230, 0xffff0000, v124
	v_fmac_f32_e32 v232, v229, v229
	v_fmac_f32_e32 v232, v230, v230
	v_lshlrev_b32_e32 v229, 16, v125
	v_and_b32_e32 v230, 0xffff0000, v125
	v_fmac_f32_e32 v232, v229, v229
	v_fmac_f32_e32 v232, v230, v230
	v_lshlrev_b32_e32 v229, 16, v126
	v_and_b32_e32 v230, 0xffff0000, v126
	v_fmac_f32_e32 v232, v229, v229
	v_fmac_f32_e32 v232, v230, v230
	v_lshlrev_b32_e32 v229, 16, v127
	v_and_b32_e32 v230, 0xffff0000, v127
	v_fmac_f32_e32 v232, v229, v229
	v_fmac_f32_e32 v232, v230, v230
	v_lshlrev_b32_e32 v229, 16, v128
	v_and_b32_e32 v230, 0xffff0000, v128
	v_fmac_f32_e32 v232, v229, v229
	v_fmac_f32_e32 v232, v230, v230
	v_lshlrev_b32_e32 v229, 16, v129
	v_and_b32_e32 v230, 0xffff0000, v129
	v_fmac_f32_e32 v232, v229, v229
	v_fmac_f32_e32 v232, v230, v230
	v_lshlrev_b32_e32 v229, 16, v130
	v_and_b32_e32 v230, 0xffff0000, v130
	v_fmac_f32_e32 v232, v229, v229
	v_fmac_f32_e32 v232, v230, v230
	v_lshlrev_b32_e32 v229, 16, v131
	v_and_b32_e32 v230, 0xffff0000, v131
	v_fmac_f32_e32 v232, v229, v229
	v_fmac_f32_e32 v232, v230, v230
	v_lshlrev_b32_e32 v229, 16, v132
	v_and_b32_e32 v230, 0xffff0000, v132
	v_fmac_f32_e32 v232, v229, v229
	v_fmac_f32_e32 v232, v230, v230
	v_lshlrev_b32_e32 v229, 16, v133
	v_and_b32_e32 v230, 0xffff0000, v133
	v_fmac_f32_e32 v232, v229, v229
	v_fmac_f32_e32 v232, v230, v230
	v_lshlrev_b32_e32 v229, 16, v134
	v_and_b32_e32 v230, 0xffff0000, v134
	v_fmac_f32_e32 v232, v229, v229
	v_fmac_f32_e32 v232, v230, v230
	v_lshlrev_b32_e32 v229, 16, v135
	v_and_b32_e32 v230, 0xffff0000, v135
	v_fmac_f32_e32 v232, v229, v229
	v_fmac_f32_e32 v232, v230, v230
	v_lshlrev_b32_e32 v229, 16, v136
	v_and_b32_e32 v230, 0xffff0000, v136
	v_fmac_f32_e32 v232, v229, v229
	v_fmac_f32_e32 v232, v230, v230
	v_lshlrev_b32_e32 v229, 16, v137
	v_and_b32_e32 v230, 0xffff0000, v137
	v_fmac_f32_e32 v232, v229, v229
	v_fmac_f32_e32 v232, v230, v230
	v_lshlrev_b32_e32 v229, 16, v138
	v_and_b32_e32 v230, 0xffff0000, v138
	v_fmac_f32_e32 v232, v229, v229
	v_fmac_f32_e32 v232, v230, v230
	v_lshlrev_b32_e32 v229, 16, v139
	v_and_b32_e32 v230, 0xffff0000, v139
	v_fmac_f32_e32 v232, v229, v229
	v_fmac_f32_e32 v232, v230, v230
	v_lshlrev_b32_e32 v229, 16, v140
	v_and_b32_e32 v230, 0xffff0000, v140
	v_fmac_f32_e32 v232, v229, v229
	v_fmac_f32_e32 v232, v230, v230
	v_lshlrev_b32_e32 v229, 16, v141
	v_and_b32_e32 v230, 0xffff0000, v141
	v_fmac_f32_e32 v232, v229, v229
	v_fmac_f32_e32 v232, v230, v230
	v_lshlrev_b32_e32 v229, 16, v142
	v_and_b32_e32 v230, 0xffff0000, v142
	v_fmac_f32_e32 v232, v229, v229
	v_fmac_f32_e32 v232, v230, v230
	v_lshlrev_b32_e32 v229, 16, v143
	v_and_b32_e32 v230, 0xffff0000, v143
	v_fmac_f32_e32 v232, v229, v229
	v_fmac_f32_e32 v232, v230, v230
	v_lshlrev_b32_e32 v229, 16, v144
	v_and_b32_e32 v230, 0xffff0000, v144
	v_mul_f32_e32 v233, v229, v229
	v_fmac_f32_e32 v233, v230, v230
	v_lshlrev_b32_e32 v229, 16, v145
	v_and_b32_e32 v230, 0xffff0000, v145
	v_fmac_f32_e32 v233, v229, v229
	v_fmac_f32_e32 v233, v230, v230
	v_lshlrev_b32_e32 v229, 16, v146
	v_and_b32_e32 v230, 0xffff0000, v146
	v_fmac_f32_e32 v233, v229, v229
	v_fmac_f32_e32 v233, v230, v230
	v_lshlrev_b32_e32 v229, 16, v147
	v_and_b32_e32 v230, 0xffff0000, v147
	v_fmac_f32_e32 v233, v229, v229
	v_fmac_f32_e32 v233, v230, v230
	v_lshlrev_b32_e32 v229, 16, v148
	v_and_b32_e32 v230, 0xffff0000, v148
	v_fmac_f32_e32 v233, v229, v229
	v_fmac_f32_e32 v233, v230, v230
	v_lshlrev_b32_e32 v229, 16, v149
	v_and_b32_e32 v230, 0xffff0000, v149
	v_fmac_f32_e32 v233, v229, v229
	v_fmac_f32_e32 v233, v230, v230
	v_lshlrev_b32_e32 v229, 16, v150
	v_and_b32_e32 v230, 0xffff0000, v150
	v_fmac_f32_e32 v233, v229, v229
	v_fmac_f32_e32 v233, v230, v230
	v_lshlrev_b32_e32 v229, 16, v151
	v_and_b32_e32 v230, 0xffff0000, v151
	v_fmac_f32_e32 v233, v229, v229
	v_fmac_f32_e32 v233, v230, v230
	v_lshlrev_b32_e32 v229, 16, v152
	v_and_b32_e32 v230, 0xffff0000, v152
	v_fmac_f32_e32 v233, v229, v229
	v_fmac_f32_e32 v233, v230, v230
; DI u32x4 pack8(const float (&f)[8]) { u32x4 w; w.x = pk2(f[0], f[1]); w.y = pk2(f[2], f[3]); w.z = pk2(f[4], f[5]); w.w = pk2(f[6], f[7]); return w; }
; template <int DQK, int KA8, int DV, bool BIAS, bool JOINT>
; DI void attn_core(LAS unsigned char* lds, const bf16_t* Qrow, const bf16_t* KpA, int ldkA, const bf16_t* KpB, int ldkB, const bf16_t* Vp, int ldv,
;                   int qb, int wid, int lane, const float* qng  , f32x16 (&O)[DV / 32]) {
;     ...
;             ssn += __shfl_xor(ssn, 32); ssr += __shfl_xor(ssr, 32);
;             const float qs = 0.07216878364870322f * LOG2E, scn = rsqrtf(ssn * (1.f / 128.f) + EPS) * qs, scr = rsqrtf(ssr * (1.f / 64.f) + EPS) * qs;
; #pragma unroll
;             for (int s = 0; s < 8; ++s) { float f[8]; unpack8(__builtin_bit_cast(u32x4, qf[s]), f);
;                 const f32x4 g0 = *(const f32x4*)(qng + 16 * s + 8 * hh), g1 = *(const f32x4*)(qng + 16 * s + 8 * hh + 4);
; #pragma unroll
;                 for (int e = 0; e < 4; ++e) { f[e] *= scn * g0[e]; f[4 + e] *= scn * g1[e]; }
;                 qf[s] = __builtin_bit_cast(bf16x8, pack8(f)); }
	v_lshlrev_b32_e32 v229, 16, v153
	v_and_b32_e32 v230, 0xffff0000, v153
	v_fmac_f32_e32 v233, v229, v229
	v_fmac_f32_e32 v233, v230, v230
	v_lshlrev_b32_e32 v229, 16, v154
	v_and_b32_e32 v230, 0xffff0000, v154
	v_fmac_f32_e32 v233, v229, v229
	v_fmac_f32_e32 v233, v230, v230
	v_lshlrev_b32_e32 v229, 16, v155
	v_and_b32_e32 v230, 0xffff0000, v155
	v_fmac_f32_e32 v233, v229, v229
	v_fmac_f32_e32 v233, v230, v230
	v_lshlrev_b32_e32 v229, 16, v156
	v_and_b32_e32 v230, 0xffff0000, v156
	v_fmac_f32_e32 v233, v229, v229
	v_fmac_f32_e32 v233, v230, v230
	v_lshlrev_b32_e32 v229, 16, v157
	v_and_b32_e32 v230, 0xffff0000, v157
	v_fmac_f32_e32 v233, v229, v229
	v_fmac_f32_e32 v233, v230, v230
	v_lshlrev_b32_e32 v229, 16, v158
	v_and_b32_e32 v230, 0xffff0000, v158
	v_fmac_f32_e32 v233, v229, v229
	v_fmac_f32_e32 v233, v230, v230
	v_lshlrev_b32_e32 v229, 16, v159
	v_and_b32_e32 v230, 0xffff0000, v159
	v_fmac_f32_e32 v233, v229, v229
	v_fmac_f32_e32 v233, v230, v230
	v_mov_b32_e32 v230, v232
	v_mov_b32_e32 v231, v232
	s_nop 1
	v_permlane32_swap_b32_e32 v230, v231
	s_nop 1
	v_add_f32_e32 v232, v230, v231
	v_mov_b32_e32 v230, v233
	v_mov_b32_e32 v231, v233
	s_nop 1
	v_permlane32_swap_b32_e32 v230, v231
	s_nop 1
	v_add_f32_e32 v233, v230, v231
	v_mul_f32_e32 v232, 0x3c000000, v232
	v_mul_f32_e32 v233, 0x3c800000, v233
	v_add_f32_e32 v232, 0x358637bd, v232
	v_add_f32_e32 v233, 0x358637bd, v233
	v_rsq_f32_e32 v232, v232
	v_rsq_f32_e32 v233, v233
	s_nop 1
	v_mul_f32_e32 v241, 0x3dd53b95, v232
	v_mul_f32_e32 v242, 0x3dd53b95, v233
	ds_read_b128 v[182:185], v239 offset:0
	ds_read_b128 v[186:189], v239 offset:16
	s_waitcnt lgkmcnt(0)
	v_lshlrev_b32_e32 v229, 16, v112
	v_and_b32_e32 v230, 0xffff0000, v112
	v_mul_f32_e32 v234, v241, v182
	v_mul_f32_e32 v235, v241, v183
	v_mul_f32_e32 v229, v229, v234
	v_mul_f32_e32 v230, v230, v235
	v_cvt_pk_bf16_f32 v112, v229, v230
	v_lshlrev_b32_e32 v229, 16, v113
	v_and_b32_e32 v230, 0xffff0000, v113
	v_mul_f32_e32 v234, v241, v184
	v_mul_f32_e32 v235, v241, v185
	v_mul_f32_e32 v229, v229, v234
	v_mul_f32_e32 v230, v230, v235
	v_cvt_pk_bf16_f32 v113, v229, v230
	v_lshlrev_b32_e32 v229, 16, v114
	v_and_b32_e32 v230, 0xffff0000, v114
	v_mul_f32_e32 v234, v241, v186
	v_mul_f32_e32 v235, v241, v187
	v_mul_f32_e32 v229, v229, v234
	v_mul_f32_e32 v230, v230, v235
	v_cvt_pk_bf16_f32 v114, v229, v230
	v_lshlrev_b32_e32 v229, 16, v115
	v_and_b32_e32 v230, 0xffff0000, v115
	v_mul_f32_e32 v234, v241, v188
	v_mul_f32_e32 v235, v241, v189
	v_mul_f32_e32 v229, v229, v234
	v_mul_f32_e32 v230, v230, v235
	v_cvt_pk_bf16_f32 v115, v229, v230
	ds_read_b128 v[182:185], v239 offset:64
	ds_read_b128 v[186:189], v239 offset:80
	s_waitcnt lgkmcnt(0)
	v_lshlrev_b32_e32 v229, 16, v116
	v_and_b32_e32 v230, 0xffff0000, v116
	v_mul_f32_e32 v234, v241, v182
	v_mul_f32_e32 v235, v241, v183
	v_mul_f32_e32 v229, v229, v234
	v_mul_f32_e32 v230, v230, v235
	v_cvt_pk_bf16_f32 v116, v229, v230
	v_lshlrev_b32_e32 v229, 16, v117
	v_and_b32_e32 v230, 0xffff0000, v117
	v_mul_f32_e32 v234, v241, v184
	v_mul_f32_e32 v235, v241, v185
	v_mul_f32_e32 v229, v229, v234
	v_mul_f32_e32 v230, v230, v235
	v_cvt_pk_bf16_f32 v117, v229, v230
	v_lshlrev_b32_e32 v229, 16, v118
	v_and_b32_e32 v230, 0xffff0000, v118
	v_mul_f32_e32 v234, v241, v186
	v_mul_f32_e32 v235, v241, v187
	v_mul_f32_e32 v229, v229, v234
	v_mul_f32_e32 v230, v230, v235
	v_cvt_pk_bf16_f32 v118, v229, v230
	v_lshlrev_b32_e32 v229, 16, v119
	v_and_b32_e32 v230, 0xffff0000, v119
	v_mul_f32_e32 v234, v241, v188
	v_mul_f32_e32 v235, v241, v189
	v_mul_f32_e32 v229, v229, v234
	v_mul_f32_e32 v230, v230, v235
	v_cvt_pk_bf16_f32 v119, v229, v230
	ds_read_b128 v[182:185], v239 offset:128
	ds_read_b128 v[186:189], v239 offset:144
	s_waitcnt lgkmcnt(0)
	v_lshlrev_b32_e32 v229, 16, v120
	v_and_b32_e32 v230, 0xffff0000, v120
	v_mul_f32_e32 v234, v241, v182
	v_mul_f32_e32 v235, v241, v183
	v_mul_f32_e32 v229, v229, v234
	v_mul_f32_e32 v230, v230, v235
	v_cvt_pk_bf16_f32 v120, v229, v230
	v_lshlrev_b32_e32 v229, 16, v121
	v_and_b32_e32 v230, 0xffff0000, v121
	v_mul_f32_e32 v234, v241, v184
	v_mul_f32_e32 v235, v241, v185
	v_mul_f32_e32 v229, v229, v234
	v_mul_f32_e32 v230, v230, v235
	v_cvt_pk_bf16_f32 v121, v229, v230
	v_lshlrev_b32_e32 v229, 16, v122
	v_and_b32_e32 v230, 0xffff0000, v122
	v_mul_f32_e32 v234, v241, v186
	v_mul_f32_e32 v235, v241, v187
	v_mul_f32_e32 v229, v229, v234
	v_mul_f32_e32 v230, v230, v235
	v_cvt_pk_bf16_f32 v122, v229, v230
	v_lshlrev_b32_e32 v229, 16, v123
	v_and_b32_e32 v230, 0xffff0000, v123
	v_mul_f32_e32 v234, v241, v188
	v_mul_f32_e32 v235, v241, v189
	v_mul_f32_e32 v229, v229, v234
	v_mul_f32_e32 v230, v230, v235
	v_cvt_pk_bf16_f32 v123, v229, v230
	ds_read_b128 v[182:185], v239 offset:192
	ds_read_b128 v[186:189], v239 offset:208
	s_waitcnt lgkmcnt(0)
	v_lshlrev_b32_e32 v229, 16, v124
	v_and_b32_e32 v230, 0xffff0000, v124
	v_mul_f32_e32 v234, v241, v182
	v_mul_f32_e32 v235, v241, v183
	v_mul_f32_e32 v229, v229, v234
	v_mul_f32_e32 v230, v230, v235
	v_cvt_pk_bf16_f32 v124, v229, v230
	v_lshlrev_b32_e32 v229, 16, v125
	v_and_b32_e32 v230, 0xffff0000, v125
	v_mul_f32_e32 v234, v241, v184
	v_mul_f32_e32 v235, v241, v185
	v_mul_f32_e32 v229, v229, v234
	v_mul_f32_e32 v230, v230, v235
	v_cvt_pk_bf16_f32 v125, v229, v230
	v_lshlrev_b32_e32 v229, 16, v126
	v_and_b32_e32 v230, 0xffff0000, v126
	v_mul_f32_e32 v234, v241, v186
	v_mul_f32_e32 v235, v241, v187
	v_mul_f32_e32 v229, v229, v234
	v_mul_f32_e32 v230, v230, v235
	v_cvt_pk_bf16_f32 v126, v229, v230
	v_lshlrev_b32_e32 v229, 16, v127
	v_and_b32_e32 v230, 0xffff0000, v127
	v_mul_f32_e32 v234, v241, v188
	v_mul_f32_e32 v235, v241, v189
	v_mul_f32_e32 v229, v229, v234
	v_mul_f32_e32 v230, v230, v235
	v_cvt_pk_bf16_f32 v127, v229, v230
	ds_read_b128 v[182:185], v239 offset:256
	ds_read_b128 v[186:189], v239 offset:272
	s_waitcnt lgkmcnt(0)
; DI u32x4 pack8(const float (&f)[8]) { u32x4 w; w.x = pk2(f[0], f[1]); w.y = pk2(f[2], f[3]); w.z = pk2(f[4], f[5]); w.w = pk2(f[6], f[7]); return w; }
; template <int DQK, int KA8, int DV, bool BIAS, bool JOINT>
; DI void attn_core(LAS unsigned char* lds, const bf16_t* Qrow, const bf16_t* KpA, int ldkA, const bf16_t* KpB, int ldkB, const bf16_t* Vp, int ldv,
;                   int qb, int wid, int lane, const float* qng  , f32x16 (&O)[DV / 32]) {
;     ...
;             for (int s = 0; s < 8; ++s) { float f[8]; unpack8(__builtin_bit_cast(u32x4, qf[s]), f);
;                 const f32x4 g0 = *(const f32x4*)(qng + 16 * s + 8 * hh), g1 = *(const f32x4*)(qng + 16 * s + 8 * hh + 4);
; #pragma unroll
;                 for (int e = 0; e < 4; ++e) { f[e] *= scn * g0[e]; f[4 + e] *= scn * g1[e]; }
;                 qf[s] = __builtin_bit_cast(bf16x8, pack8(f)); }
;             const float posr = (float)(qb * 256 + wid * 32 + l32) * 0.15915494309189535f;
; #pragma unroll
;             for (int s = 8; s < 10; ++s) { float f1[8], f2[8]; unpack8(__builtin_bit_cast(u32x4, qf[s]), f1); unpack8(__builtin_bit_cast(u32x4, qf[s + 2]), f2);
; #pragma unroll
;                 for (int e = 0; e < 8; ++e) { const int i = 16 * (s - 8) + 8 * hh + e;
;                     const float a1 = f1[e] * scr * qng[128 + i], a2 = f2[e] * scr * qng[160 + i];
	v_lshlrev_b32_e32 v229, 16, v128
	v_and_b32_e32 v230, 0xffff0000, v128
	v_mul_f32_e32 v234, v241, v182
	v_mul_f32_e32 v235, v241, v183
	v_mul_f32_e32 v229, v229, v234
	v_mul_f32_e32 v230, v230, v235
	v_cvt_pk_bf16_f32 v128, v229, v230
	v_lshlrev_b32_e32 v229, 16, v129
	v_and_b32_e32 v230, 0xffff0000, v129
	v_mul_f32_e32 v234, v241, v184
	v_mul_f32_e32 v235, v241, v185
	v_mul_f32_e32 v229, v229, v234
	v_mul_f32_e32 v230, v230, v235
	v_cvt_pk_bf16_f32 v129, v229, v230
	v_lshlrev_b32_e32 v229, 16, v130
	v_and_b32_e32 v230, 0xffff0000, v130
	v_mul_f32_e32 v234, v241, v186
	v_mul_f32_e32 v235, v241, v187
	v_mul_f32_e32 v229, v229, v234
	v_mul_f32_e32 v230, v230, v235
	v_cvt_pk_bf16_f32 v130, v229, v230
	v_lshlrev_b32_e32 v229, 16, v131
	v_and_b32_e32 v230, 0xffff0000, v131
	v_mul_f32_e32 v234, v241, v188
	v_mul_f32_e32 v235, v241, v189
	v_mul_f32_e32 v229, v229, v234
	v_mul_f32_e32 v230, v230, v235
	v_cvt_pk_bf16_f32 v131, v229, v230
	ds_read_b128 v[182:185], v239 offset:320
	ds_read_b128 v[186:189], v239 offset:336
	s_waitcnt lgkmcnt(0)
	v_lshlrev_b32_e32 v229, 16, v132
	v_and_b32_e32 v230, 0xffff0000, v132
	v_mul_f32_e32 v234, v241, v182
	v_mul_f32_e32 v235, v241, v183
	v_mul_f32_e32 v229, v229, v234
	v_mul_f32_e32 v230, v230, v235
	v_cvt_pk_bf16_f32 v132, v229, v230
	v_lshlrev_b32_e32 v229, 16, v133
	v_and_b32_e32 v230, 0xffff0000, v133
	v_mul_f32_e32 v234, v241, v184
	v_mul_f32_e32 v235, v241, v185
	v_mul_f32_e32 v229, v229, v234
	v_mul_f32_e32 v230, v230, v235
	v_cvt_pk_bf16_f32 v133, v229, v230
	v_lshlrev_b32_e32 v229, 16, v134
	v_and_b32_e32 v230, 0xffff0000, v134
	v_mul_f32_e32 v234, v241, v186
	v_mul_f32_e32 v235, v241, v187
	v_mul_f32_e32 v229, v229, v234
	v_mul_f32_e32 v230, v230, v235
	v_cvt_pk_bf16_f32 v134, v229, v230
	v_lshlrev_b32_e32 v229, 16, v135
	v_and_b32_e32 v230, 0xffff0000, v135
	v_mul_f32_e32 v234, v241, v188
	v_mul_f32_e32 v235, v241, v189
	v_mul_f32_e32 v229, v229, v234
	v_mul_f32_e32 v230, v230, v235
	v_cvt_pk_bf16_f32 v135, v229, v230
	ds_read_b128 v[182:185], v239 offset:384
	ds_read_b128 v[186:189], v239 offset:400
	s_waitcnt lgkmcnt(0)
	v_lshlrev_b32_e32 v229, 16, v136
	v_and_b32_e32 v230, 0xffff0000, v136
	v_mul_f32_e32 v234, v241, v182
	v_mul_f32_e32 v235, v241, v183
	v_mul_f32_e32 v229, v229, v234
	v_mul_f32_e32 v230, v230, v235
	v_cvt_pk_bf16_f32 v136, v229, v230
	v_lshlrev_b32_e32 v229, 16, v137
	v_and_b32_e32 v230, 0xffff0000, v137
	v_mul_f32_e32 v234, v241, v184
	v_mul_f32_e32 v235, v241, v185
	v_mul_f32_e32 v229, v229, v234
	v_mul_f32_e32 v230, v230, v235
	v_cvt_pk_bf16_f32 v137, v229, v230
	v_lshlrev_b32_e32 v229, 16, v138
	v_and_b32_e32 v230, 0xffff0000, v138
	v_mul_f32_e32 v234, v241, v186
	v_mul_f32_e32 v235, v241, v187
	v_mul_f32_e32 v229, v229, v234
	v_mul_f32_e32 v230, v230, v235
	v_cvt_pk_bf16_f32 v138, v229, v230
	v_lshlrev_b32_e32 v229, 16, v139
	v_and_b32_e32 v230, 0xffff0000, v139
	v_mul_f32_e32 v234, v241, v188
	v_mul_f32_e32 v235, v241, v189
	v_mul_f32_e32 v229, v229, v234
	v_mul_f32_e32 v230, v230, v235
	v_cvt_pk_bf16_f32 v139, v229, v230
	ds_read_b128 v[182:185], v239 offset:448
	ds_read_b128 v[186:189], v239 offset:464
	s_waitcnt lgkmcnt(0)
	v_lshlrev_b32_e32 v229, 16, v140
	v_and_b32_e32 v230, 0xffff0000, v140
	v_mul_f32_e32 v234, v241, v182
	v_mul_f32_e32 v235, v241, v183
	v_mul_f32_e32 v229, v229, v234
	v_mul_f32_e32 v230, v230, v235
	v_cvt_pk_bf16_f32 v140, v229, v230
	v_lshlrev_b32_e32 v229, 16, v141
	v_and_b32_e32 v230, 0xffff0000, v141
	v_mul_f32_e32 v234, v241, v184
	v_mul_f32_e32 v235, v241, v185
	v_mul_f32_e32 v229, v229, v234
	v_mul_f32_e32 v230, v230, v235
	v_cvt_pk_bf16_f32 v141, v229, v230
	v_lshlrev_b32_e32 v229, 16, v142
	v_and_b32_e32 v230, 0xffff0000, v142
	v_mul_f32_e32 v234, v241, v186
	v_mul_f32_e32 v235, v241, v187
	v_mul_f32_e32 v229, v229, v234
	v_mul_f32_e32 v230, v230, v235
	v_cvt_pk_bf16_f32 v142, v229, v230
	v_lshlrev_b32_e32 v229, 16, v143
	v_and_b32_e32 v230, 0xffff0000, v143
	v_mul_f32_e32 v234, v241, v188
	v_mul_f32_e32 v235, v241, v189
	v_mul_f32_e32 v229, v229, v234
	v_mul_f32_e32 v230, v230, v235
	v_cvt_pk_bf16_f32 v143, v229, v230
	ds_read_b128 v[182:185], v239 offset:512
	ds_read_b128 v[186:189], v239 offset:528
	ds_read_b128 v[190:193], v239 offset:640
	ds_read_b128 v[194:197], v239 offset:656
	s_waitcnt lgkmcnt(0)
; DI u32x4 pack8(const float (&f)[8]) { u32x4 w; w.x = pk2(f[0], f[1]); w.y = pk2(f[2], f[3]); w.z = pk2(f[4], f[5]); w.w = pk2(f[6], f[7]); return w; }
; template <int DQK, int KA8, int DV, bool BIAS, bool JOINT>
; DI void attn_core(LAS unsigned char* lds, const bf16_t* Qrow, const bf16_t* KpA, int ldkA, const bf16_t* KpB, int ldkB, const bf16_t* Vp, int ldv,
;                   int qb, int wid, int lane, const float* qng  , f32x16 (&O)[DV / 32]) {
;     ...
;             const float posr = (float)(qb * 256 + wid * 32 + l32) * 0.15915494309189535f;
; #pragma unroll
;             for (int s = 8; s < 10; ++s) { float f1[8], f2[8]; unpack8(__builtin_bit_cast(u32x4, qf[s]), f1); unpack8(__builtin_bit_cast(u32x4, qf[s + 2]), f2);
; #pragma unroll
;                 for (int e = 0; e < 8; ++e) { const int i = 16 * (s - 8) + 8 * hh + e;
;                     const float a1 = f1[e] * scr * qng[128 + i], a2 = f2[e] * scr * qng[160 + i];
;                     float rev = posr * __builtin_amdgcn_exp2f(-(float)i * 0.41524101186092029f); rev -= floorf(rev);
;                     const float sn = __builtin_amdgcn_sinf(rev), cs = __builtin_amdgcn_cosf(rev);
;                     f1[e] = a1 * cs - a2 * sn; f2[e] = a2 * cs + a1 * sn; }
;                 qf[s] = __builtin_bit_cast(bf16x8, pack8(f1)); qf[s + 2] = __builtin_bit_cast(bf16x8, pack8(f2)); }
	v_lshl_add_u32 v229, v227, 3, 0
	v_cvt_f32_u32_e32 v229, v229
	v_mul_f32_e32 v229, 0xbed49a78, v229
	v_exp_f32_e32 v229, v229
	v_lshlrev_b32_e32 v234, 16, v144
	v_lshlrev_b32_e32 v235, 16, v152
	v_mul_f32_e32 v229, v240, v229
	v_mul_f32_e32 v234, v234, v242
	v_mul_f32_e32 v235, v235, v242
	v_fract_f32_e32 v229, v229
	v_mul_f32_e32 v234, v234, v182
	v_mul_f32_e32 v235, v235, v190
	v_sin_f32_e32 v230, v229
	v_cos_f32_e32 v231, v229
	s_nop 1
	v_mul_f32_e32 v236, v235, v230
	v_mul_f32_e32 v233, v234, v230
	v_fma_f32 v243, v234, v231, -v236
	v_fma_f32 v245, v235, v231, v233
	v_lshl_add_u32 v229, v227, 3, 1
	v_cvt_f32_u32_e32 v229, v229
	v_mul_f32_e32 v229, 0xbed49a78, v229
	v_exp_f32_e32 v229, v229
	v_and_b32_e32 v234, 0xffff0000, v144
	v_and_b32_e32 v235, 0xffff0000, v152
	v_mul_f32_e32 v229, v240, v229
	v_mul_f32_e32 v234, v234, v242
	v_mul_f32_e32 v235, v235, v242
	v_fract_f32_e32 v229, v229
	v_mul_f32_e32 v234, v234, v183
	v_mul_f32_e32 v235, v235, v191
	v_sin_f32_e32 v230, v229
	v_cos_f32_e32 v231, v229
	s_nop 1
	v_mul_f32_e32 v236, v235, v230
	v_mul_f32_e32 v233, v234, v230
	v_fma_f32 v244, v234, v231, -v236
	v_fma_f32 v246, v235, v231, v233
	v_cvt_pk_bf16_f32 v144, v243, v244
	v_cvt_pk_bf16_f32 v152, v245, v246
	v_lshl_add_u32 v229, v227, 3, 2
	v_cvt_f32_u32_e32 v229, v229
	v_mul_f32_e32 v229, 0xbed49a78, v229
	v_exp_f32_e32 v229, v229
	v_lshlrev_b32_e32 v234, 16, v145
	v_lshlrev_b32_e32 v235, 16, v153
	v_mul_f32_e32 v229, v240, v229
	v_mul_f32_e32 v234, v234, v242
	v_mul_f32_e32 v235, v235, v242
	v_fract_f32_e32 v229, v229
	v_mul_f32_e32 v234, v234, v184
	v_mul_f32_e32 v235, v235, v192
	v_sin_f32_e32 v230, v229
	v_cos_f32_e32 v231, v229
	s_nop 1
	v_mul_f32_e32 v236, v235, v230
	v_mul_f32_e32 v233, v234, v230
	v_fma_f32 v243, v234, v231, -v236
	v_fma_f32 v245, v235, v231, v233
	v_lshl_add_u32 v229, v227, 3, 3
	v_cvt_f32_u32_e32 v229, v229
	v_mul_f32_e32 v229, 0xbed49a78, v229
	v_exp_f32_e32 v229, v229
	v_and_b32_e32 v234, 0xffff0000, v145
	v_and_b32_e32 v235, 0xffff0000, v153
	v_mul_f32_e32 v229, v240, v229
	v_mul_f32_e32 v234, v234, v242
	v_mul_f32_e32 v235, v235, v242
	v_fract_f32_e32 v229, v229
	v_mul_f32_e32 v234, v234, v185
	v_mul_f32_e32 v235, v235, v193
	v_sin_f32_e32 v230, v229
	v_cos_f32_e32 v231, v229
	s_nop 1
	v_mul_f32_e32 v236, v235, v230
	v_mul_f32_e32 v233, v234, v230
	v_fma_f32 v244, v234, v231, -v236
	v_fma_f32 v246, v235, v231, v233
	v_cvt_pk_bf16_f32 v145, v243, v244
	v_cvt_pk_bf16_f32 v153, v245, v246
	v_lshl_add_u32 v229, v227, 3, 4
	v_cvt_f32_u32_e32 v229, v229
	v_mul_f32_e32 v229, 0xbed49a78, v229
	v_exp_f32_e32 v229, v229
	v_lshlrev_b32_e32 v234, 16, v146
	v_lshlrev_b32_e32 v235, 16, v154
	v_mul_f32_e32 v229, v240, v229
	v_mul_f32_e32 v234, v234, v242
	v_mul_f32_e32 v235, v235, v242
	v_fract_f32_e32 v229, v229
	v_mul_f32_e32 v234, v234, v186
	v_mul_f32_e32 v235, v235, v194
	v_sin_f32_e32 v230, v229
	v_cos_f32_e32 v231, v229
	s_nop 1
	v_mul_f32_e32 v236, v235, v230
	v_mul_f32_e32 v233, v234, v230
	v_fma_f32 v243, v234, v231, -v236
	v_fma_f32 v245, v235, v231, v233
	v_lshl_add_u32 v229, v227, 3, 5
	v_cvt_f32_u32_e32 v229, v229
	v_mul_f32_e32 v229, 0xbed49a78, v229
	v_exp_f32_e32 v229, v229
	v_and_b32_e32 v234, 0xffff0000, v146
	v_and_b32_e32 v235, 0xffff0000, v154
	v_mul_f32_e32 v229, v240, v229
	v_mul_f32_e32 v234, v234, v242
	v_mul_f32_e32 v235, v235, v242
	v_fract_f32_e32 v229, v229
	v_mul_f32_e32 v234, v234, v187
	v_mul_f32_e32 v235, v235, v195
	v_sin_f32_e32 v230, v229
	v_cos_f32_e32 v231, v229
	s_nop 1
	v_mul_f32_e32 v236, v235, v230
	v_mul_f32_e32 v233, v234, v230
	v_fma_f32 v244, v234, v231, -v236
	v_fma_f32 v246, v235, v231, v233
	v_cvt_pk_bf16_f32 v146, v243, v244
	v_cvt_pk_bf16_f32 v154, v245, v246
	v_lshl_add_u32 v229, v227, 3, 6
	v_cvt_f32_u32_e32 v229, v229
	v_mul_f32_e32 v229, 0xbed49a78, v229
	v_exp_f32_e32 v229, v229
	v_lshlrev_b32_e32 v234, 16, v147
	v_lshlrev_b32_e32 v235, 16, v155
	v_mul_f32_e32 v229, v240, v229
	v_mul_f32_e32 v234, v234, v242
	v_mul_f32_e32 v235, v235, v242
	v_fract_f32_e32 v229, v229
	v_mul_f32_e32 v234, v234, v188
	v_mul_f32_e32 v235, v235, v196
	v_sin_f32_e32 v230, v229
	v_cos_f32_e32 v231, v229
	s_nop 1
	v_mul_f32_e32 v236, v235, v230
	v_mul_f32_e32 v233, v234, v230
	v_fma_f32 v243, v234, v231, -v236
	v_fma_f32 v245, v235, v231, v233
	v_lshl_add_u32 v229, v227, 3, 7
	v_cvt_f32_u32_e32 v229, v229
	v_mul_f32_e32 v229, 0xbed49a78, v229
	v_exp_f32_e32 v229, v229
	v_and_b32_e32 v234, 0xffff0000, v147
	v_and_b32_e32 v235, 0xffff0000, v155
	v_mul_f32_e32 v229, v240, v229
	v_mul_f32_e32 v234, v234, v242
	v_mul_f32_e32 v235, v235, v242
	v_fract_f32_e32 v229, v229
	v_mul_f32_e32 v234, v234, v189
	v_mul_f32_e32 v235, v235, v197
	v_sin_f32_e32 v230, v229
	v_cos_f32_e32 v231, v229
	s_nop 1
	v_mul_f32_e32 v236, v235, v230
	v_mul_f32_e32 v233, v234, v230
	v_fma_f32 v244, v234, v231, -v236
	v_fma_f32 v246, v235, v231, v233
	v_cvt_pk_bf16_f32 v147, v243, v244
	v_cvt_pk_bf16_f32 v155, v245, v246
	ds_read_b128 v[182:185], v239 offset:576
	ds_read_b128 v[186:189], v239 offset:592
	ds_read_b128 v[190:193], v239 offset:704
	ds_read_b128 v[194:197], v239 offset:720
	s_waitcnt lgkmcnt(0)
; DI u32x4 pack8(const float (&f)[8]) { u32x4 w; w.x = pk2(f[0], f[1]); w.y = pk2(f[2], f[3]); w.z = pk2(f[4], f[5]); w.w = pk2(f[6], f[7]); return w; }
; template <int DQK, int KA8, int DV, bool BIAS, bool JOINT>
; DI void attn_core(LAS unsigned char* lds, const bf16_t* Qrow, const bf16_t* KpA, int ldkA, const bf16_t* KpB, int ldkB, const bf16_t* Vp, int ldv,
;                   int qb, int wid, int lane, const float* qng  , f32x16 (&O)[DV / 32]) {
;     ...
; #pragma unroll
;             for (int s = 8; s < 10; ++s) { float f1[8], f2[8]; unpack8(__builtin_bit_cast(u32x4, qf[s]), f1); unpack8(__builtin_bit_cast(u32x4, qf[s + 2]), f2);
; #pragma unroll
;                 for (int e = 0; e < 8; ++e) { const int i = 16 * (s - 8) + 8 * hh + e;
;                     const float a1 = f1[e] * scr * qng[128 + i], a2 = f2[e] * scr * qng[160 + i];
;                     float rev = posr * __builtin_amdgcn_exp2f(-(float)i * 0.41524101186092029f); rev -= floorf(rev);
;                     const float sn = __builtin_amdgcn_sinf(rev), cs = __builtin_amdgcn_cosf(rev);
;                     f1[e] = a1 * cs - a2 * sn; f2[e] = a2 * cs + a1 * sn; }
;                 qf[s] = __builtin_bit_cast(bf16x8, pack8(f1)); qf[s + 2] = __builtin_bit_cast(bf16x8, pack8(f2)); }
;             __builtin_amdgcn_sched_barrier(0);
	v_lshl_add_u32 v229, v227, 3, 16
	v_cvt_f32_u32_e32 v229, v229
	v_mul_f32_e32 v229, 0xbed49a78, v229
	v_exp_f32_e32 v229, v229
	v_lshlrev_b32_e32 v234, 16, v148
	v_lshlrev_b32_e32 v235, 16, v156
	v_mul_f32_e32 v229, v240, v229
	v_mul_f32_e32 v234, v234, v242
	v_mul_f32_e32 v235, v235, v242
	v_fract_f32_e32 v229, v229
	v_mul_f32_e32 v234, v234, v182
	v_mul_f32_e32 v235, v235, v190
	v_sin_f32_e32 v230, v229
	v_cos_f32_e32 v231, v229
	s_nop 1
	v_mul_f32_e32 v236, v235, v230
	v_mul_f32_e32 v233, v234, v230
	v_fma_f32 v243, v234, v231, -v236
	v_fma_f32 v245, v235, v231, v233
	v_lshl_add_u32 v229, v227, 3, 17
	v_cvt_f32_u32_e32 v229, v229
	v_mul_f32_e32 v229, 0xbed49a78, v229
	v_exp_f32_e32 v229, v229
	v_and_b32_e32 v234, 0xffff0000, v148
	v_and_b32_e32 v235, 0xffff0000, v156
	v_mul_f32_e32 v229, v240, v229
	v_mul_f32_e32 v234, v234, v242
	v_mul_f32_e32 v235, v235, v242
	v_fract_f32_e32 v229, v229
	v_mul_f32_e32 v234, v234, v183
	v_mul_f32_e32 v235, v235, v191
	v_sin_f32_e32 v230, v229
	v_cos_f32_e32 v231, v229
	s_nop 1
	v_mul_f32_e32 v236, v235, v230
	v_mul_f32_e32 v233, v234, v230
	v_fma_f32 v244, v234, v231, -v236
	v_fma_f32 v246, v235, v231, v233
	v_cvt_pk_bf16_f32 v148, v243, v244
	v_cvt_pk_bf16_f32 v156, v245, v246
	v_lshl_add_u32 v229, v227, 3, 18
	v_cvt_f32_u32_e32 v229, v229
	v_mul_f32_e32 v229, 0xbed49a78, v229
	v_exp_f32_e32 v229, v229
	v_lshlrev_b32_e32 v234, 16, v149
	v_lshlrev_b32_e32 v235, 16, v157
	v_mul_f32_e32 v229, v240, v229
	v_mul_f32_e32 v234, v234, v242
	v_mul_f32_e32 v235, v235, v242
	v_fract_f32_e32 v229, v229
	v_mul_f32_e32 v234, v234, v184
	v_mul_f32_e32 v235, v235, v192
	v_sin_f32_e32 v230, v229
	v_cos_f32_e32 v231, v229
	s_nop 1
	v_mul_f32_e32 v236, v235, v230
	v_mul_f32_e32 v233, v234, v230
	v_fma_f32 v243, v234, v231, -v236
	v_fma_f32 v245, v235, v231, v233
	v_lshl_add_u32 v229, v227, 3, 19
	v_cvt_f32_u32_e32 v229, v229
	v_mul_f32_e32 v229, 0xbed49a78, v229
	v_exp_f32_e32 v229, v229
	v_and_b32_e32 v234, 0xffff0000, v149
	v_and_b32_e32 v235, 0xffff0000, v157
	v_mul_f32_e32 v229, v240, v229
	v_mul_f32_e32 v234, v234, v242
	v_mul_f32_e32 v235, v235, v242
	v_fract_f32_e32 v229, v229
	v_mul_f32_e32 v234, v234, v185
	v_mul_f32_e32 v235, v235, v193
	v_sin_f32_e32 v230, v229
	v_cos_f32_e32 v231, v229
	s_nop 1
	v_mul_f32_e32 v236, v235, v230
	v_mul_f32_e32 v233, v234, v230
	v_fma_f32 v244, v234, v231, -v236
	v_fma_f32 v246, v235, v231, v233
	v_cvt_pk_bf16_f32 v149, v243, v244
	v_cvt_pk_bf16_f32 v157, v245, v246
	v_lshl_add_u32 v229, v227, 3, 20
	v_cvt_f32_u32_e32 v229, v229
	v_mul_f32_e32 v229, 0xbed49a78, v229
	v_exp_f32_e32 v229, v229
	v_lshlrev_b32_e32 v234, 16, v150
	v_lshlrev_b32_e32 v235, 16, v158
	v_mul_f32_e32 v229, v240, v229
	v_mul_f32_e32 v234, v234, v242
	v_mul_f32_e32 v235, v235, v242
	v_fract_f32_e32 v229, v229
	v_mul_f32_e32 v234, v234, v186
	v_mul_f32_e32 v235, v235, v194
	v_sin_f32_e32 v230, v229
	v_cos_f32_e32 v231, v229
	s_nop 1
	v_mul_f32_e32 v236, v235, v230
	v_mul_f32_e32 v233, v234, v230
	v_fma_f32 v243, v234, v231, -v236
	v_fma_f32 v245, v235, v231, v233
	v_lshl_add_u32 v229, v227, 3, 21
	v_cvt_f32_u32_e32 v229, v229
	v_mul_f32_e32 v229, 0xbed49a78, v229
	v_exp_f32_e32 v229, v229
	v_and_b32_e32 v234, 0xffff0000, v150
	v_and_b32_e32 v235, 0xffff0000, v158
	v_mul_f32_e32 v229, v240, v229
	v_mul_f32_e32 v234, v234, v242
	v_mul_f32_e32 v235, v235, v242
	v_fract_f32_e32 v229, v229
	v_mul_f32_e32 v234, v234, v187
	v_mul_f32_e32 v235, v235, v195
	v_sin_f32_e32 v230, v229
	v_cos_f32_e32 v231, v229
	s_nop 1
	v_mul_f32_e32 v236, v235, v230
	v_mul_f32_e32 v233, v234, v230
	v_fma_f32 v244, v234, v231, -v236
	v_fma_f32 v246, v235, v231, v233
	v_cvt_pk_bf16_f32 v150, v243, v244
	v_cvt_pk_bf16_f32 v158, v245, v246
	v_lshl_add_u32 v229, v227, 3, 22
	v_cvt_f32_u32_e32 v229, v229
	v_mul_f32_e32 v229, 0xbed49a78, v229
	v_exp_f32_e32 v229, v229
	v_lshlrev_b32_e32 v234, 16, v151
	v_lshlrev_b32_e32 v235, 16, v159
	v_mul_f32_e32 v229, v240, v229
	v_mul_f32_e32 v234, v234, v242
	v_mul_f32_e32 v235, v235, v242
	v_fract_f32_e32 v229, v229
	v_mul_f32_e32 v234, v234, v188
	v_mul_f32_e32 v235, v235, v196
	v_sin_f32_e32 v230, v229
	v_cos_f32_e32 v231, v229
	s_nop 1
	v_mul_f32_e32 v236, v235, v230
	v_mul_f32_e32 v233, v234, v230
	v_fma_f32 v243, v234, v231, -v236
	v_fma_f32 v245, v235, v231, v233
	v_lshl_add_u32 v229, v227, 3, 23
	v_cvt_f32_u32_e32 v229, v229
	v_mul_f32_e32 v229, 0xbed49a78, v229
	v_exp_f32_e32 v229, v229
	v_and_b32_e32 v234, 0xffff0000, v151
	v_and_b32_e32 v235, 0xffff0000, v159
	v_mul_f32_e32 v229, v240, v229
	v_mul_f32_e32 v234, v234, v242
	v_mul_f32_e32 v235, v235, v242
	v_fract_f32_e32 v229, v229
	v_mul_f32_e32 v234, v234, v189
	v_mul_f32_e32 v235, v235, v197
	v_sin_f32_e32 v230, v229
	v_cos_f32_e32 v231, v229
	s_nop 1
	v_mul_f32_e32 v236, v235, v230
	v_mul_f32_e32 v233, v234, v230
	v_fma_f32 v244, v234, v231, -v236
	v_fma_f32 v246, v235, v231, v233
	v_cvt_pk_bf16_f32 v151, v243, v244
	v_cvt_pk_bf16_f32 v159, v245, v246
	s_barrier
	s_cmp_lt_u32 s26, 4
	s_cbranch_scc1 .Lad_nostag
	s_barrier

; template <int DQK, int KA8, int DV, bool BIAS, bool JOINT>
; DI void attn_core(LAS unsigned char* lds, const bf16_t* Qrow, const bf16_t* KpA, int ldkA, const bf16_t* KpB, int ldkB, const bf16_t* Vp, int ldv,
;                   int qb, int wid, int lane, const float* qng  , f32x16 (&O)[DV / 32]) {
;     ...
;     auto gload = [&](int kt) {
; #pragma unroll
;         for (int i = 0; i < NL; ++i) { const int c = tid + i * 512;
;             if (i * 512 < NKC) { const int row = c / KC, cc = c % KC;
;                 const bf16_t* src = (cc < KA8) ? KpA + (size_t)(kt * 64 + row) * ldkA + cc * 8 : KpB + (size_t)(kt * 64 + row) * ldkB + (cc - KA8) * 8;
;                 stg[i] = *(const u32x4*)src; }
;             else { const int c2 = c - NKC, row = c2 / VC, cc = c2 % VC; stg[i] = *(const u32x4*)(Vp + (size_t)(kt * 64 + row) * ldv + cc * 8); } }
;     };
;     auto lstore = [&](int buf) {
; #pragma unroll
;         for (int i = 0; i < NL; ++i) { const int c = tid + i * 512;
;             if (i * 512 < NKC) { const int row = c / KC, cc = c % KC; *(LAS u32x4*)(lds + buf * STG + row * KROW + cc * 16) = stg[i]; }
;             else { const int c2 = c - NKC, row = c2 / VC, cc = c2 % VC; *(LAS u32x4*)(lds + buf * STG + 64 * KROW + row * VROW + cc * 16) = stg[i]; } }
;     };
;     gload(0); lstore(0); __syncthreads();
;     for (int kt = 0; kt < nkt; ++kt) {
;         if (kt + 1 < nkt) gload(kt + 1);
;         if (JOINT && kt <= myc) {
;             LAS unsigned char* kb = lds + (kt & 1) * STG; LAS unsigned char* vb = kb + 64 * KROW;
;             const bool far = (kt * 64 + 63 - q0w <= -91);
;             f32x16 S0, S1;
; #pragma unroll
;             for (int i = 0; i < 16; ++i) { S0[i] = 0.f; S1[i] = 0.f; }
; #pragma unroll
;             for (int s = 0; s < DQK / 16; ++s) {
;                 const bf16x8 k0 = *(LAS const bf16x8*)(kb + koff + 32 * s), k1 = *(LAS const bf16x8*)(kb + koff + 32 * KROW + 32 * s);
;                 S0 = mfma32(k0, qf[s], S0); S1 = mfma32(k1, qf[s], S1);
;             }
;     ...
;             for (int half = 0; half < 2; ++half)
; #pragma unroll
;                 for (int s = 0; s < 2; ++s) {
;                     const f32x16& S = half ? S1 : S0;
;                     u32x4 pw; pw.x = pk2(S[8 * s], S[8 * s + 1]); pw.y = pk2(S[8 * s + 2], S[8 * s + 3]); pw.z = pk2(S[8 * s + 4], S[8 * s + 5]); pw.w = pk2(S[8 * s + 6], S[8 * s + 7]);
.Lad_hv_1:
	ds_write_b128 v218, v[172:175] offset:0
	ds_write_b128 v218, v[176:179] offset:10240
	s_cbranch_scc0 .Lad_hn_2
	global_load_dwordx4 v[172:175], v222, s[34:35]
	global_load_dwordx4 v[176:179], v223, s[34:35]
	s_add_u32 s34, s34, 0xe0000
	s_addc_u32 s35, s35, 0
	s_add_i32 s58, s24, 2
	s_cmp_lt_u32 s58, s17
	s_cbranch_scc0 .Lad_hn_2
	global_load_dwordx4 v[160:163], v219, s[30:31]
	global_load_dwordx4 v[164:167], v220, s[30:31]
	global_load_dwordx4 v[168:171], v221, s[36:37]
	s_add_u32 s30, s30, 0xe0000
	s_addc_u32 s31, s31, 0
	s_add_u32 s36, s36, 0x22000
	s_addc_u32 s37, s37, 0
.Lad_hn_2:
	ds_read_b64_tr_b16 v[186:187], v215 offset:30784
	ds_read_b64_tr_b16 v[188:189], v215 offset:33344
	s_waitcnt lgkmcnt(12)
	v_mfma_f32_32x32x16_bf16 v[0:15], v[198:201], v[100:103], v[0:15]
	ds_read_b64_tr_b16 v[190:191], v215 offset:30848
	ds_read_b64_tr_b16 v[192:193], v215 offset:33408
	s_waitcnt lgkmcnt(12)
	v_mfma_f32_32x32x16_bf16 v[16:31], v[202:205], v[100:103], v[16:31]
	ds_read_b64_tr_b16 v[194:195], v215 offset:30912
	ds_read_b64_tr_b16 v[196:197], v215 offset:33472
	s_waitcnt lgkmcnt(12)
	v_mfma_f32_32x32x16_bf16 v[32:47], v[206:209], v[100:103], v[32:47]
	ds_read_b64_tr_b16 v[198:199], v215 offset:35840
	ds_read_b64_tr_b16 v[200:201], v215 offset:38400
	s_waitcnt lgkmcnt(12)
	v_mfma_f32_32x32x16_bf16 v[48:63], v[210:213], v[100:103], v[48:63]
	ds_read_b64_tr_b16 v[202:203], v215 offset:35904
	ds_read_b64_tr_b16 v[204:205], v215 offset:38464
	s_waitcnt lgkmcnt(12)
	v_mfma_f32_32x32x16_bf16 v[0:15], v[182:185], v[104:107], v[0:15]
	ds_read_b64_tr_b16 v[206:207], v215 offset:35968
	ds_read_b64_tr_b16 v[208:209], v215 offset:38528
	s_waitcnt lgkmcnt(10)
	v_mfma_f32_32x32x16_bf16 v[16:31], v[186:189], v[104:107], v[16:31]
	ds_read_b64_tr_b16 v[210:211], v215 offset:36032
	ds_read_b64_tr_b16 v[212:213], v215 offset:38592
	s_waitcnt lgkmcnt(10)
	v_mfma_f32_32x32x16_bf16 v[32:47], v[190:193], v[104:107], v[32:47]
	ds_read_b128 v[182:185], v214 offset:40960
	s_waitcnt lgkmcnt(9)
	v_mfma_f32_32x32x16_bf16 v[48:63], v[194:197], v[104:107], v[48:63]
	ds_read_b128 v[186:189], v214 offset:53760
	s_waitcnt lgkmcnt(8)
	v_mfma_f32_32x32x16_bf16 v[0:15], v[198:201], v[108:111], v[0:15]
	ds_read_b128 v[190:193], v214 offset:40992
	s_waitcnt lgkmcnt(7)
	v_mfma_f32_32x32x16_bf16 v[16:31], v[202:205], v[108:111], v[16:31]
	ds_read_b128 v[194:197], v214 offset:53792
	s_waitcnt lgkmcnt(6)
	v_mfma_f32_32x32x16_bf16 v[32:47], v[206:209], v[108:111], v[32:47]
	ds_read_b128 v[198:201], v214 offset:41024
	s_waitcnt lgkmcnt(5)
	v_mfma_f32_32x32x16_bf16 v[48:63], v[210:213], v[108:111], v[48:63]
	ds_read_b128 v[202:205], v214 offset:53824
	s_waitcnt lgkmcnt(5)
	v_mfma_f32_32x32x16_bf16 v[64:79], v[182:185], v[112:115], 0
	ds_read_b128 v[206:209], v214 offset:41056
	s_waitcnt lgkmcnt(5)
	v_mfma_f32_32x32x16_bf16 v[80:95], v[186:189], v[112:115], 0
	ds_read_b128 v[210:213], v214 offset:53856
	s_waitcnt lgkmcnt(5)
	v_mfma_f32_32x32x16_bf16 v[64:79], v[190:193], v[116:119], v[64:79]
	ds_read_b128 v[182:185], v214 offset:41088
	s_waitcnt lgkmcnt(5)
	v_mfma_f32_32x32x16_bf16 v[80:95], v[194:197], v[116:119], v[80:95]
	ds_read_b128 v[186:189], v214 offset:53888
	s_waitcnt lgkmcnt(5)
	v_mfma_f32_32x32x16_bf16 v[64:79], v[198:201], v[120:123], v[64:79]
	ds_read_b128 v[190:193], v214 offset:41120
	s_waitcnt lgkmcnt(5)
	v_mfma_f32_32x32x16_bf16 v[80:95], v[202:205], v[120:123], v[80:95]
	ds_read_b128 v[194:197], v214 offset:53920
	s_waitcnt lgkmcnt(5)
	v_mfma_f32_32x32x16_bf16 v[64:79], v[206:209], v[124:127], v[64:79]
	ds_read_b128 v[198:201], v214 offset:41152
	s_waitcnt lgkmcnt(5)
	v_mfma_f32_32x32x16_bf16 v[80:95], v[210:213], v[124:127], v[80:95]
	ds_read_b128 v[202:205], v214 offset:53952
	s_waitcnt lgkmcnt(5)
	v_mfma_f32_32x32x16_bf16 v[64:79], v[182:185], v[128:131], v[64:79]
	ds_read_b128 v[206:209], v214 offset:41184
	s_waitcnt lgkmcnt(5)
	v_mfma_f32_32x32x16_bf16 v[80:95], v[186:189], v[128:131], v[80:95]
	ds_read_b128 v[210:213], v214 offset:53984
	s_waitcnt lgkmcnt(5)
	v_mfma_f32_32x32x16_bf16 v[64:79], v[190:193], v[132:135], v[64:79]
	ds_read_b128 v[182:185], v214 offset:41216
	s_waitcnt lgkmcnt(5)
	v_mfma_f32_32x32x16_bf16 v[80:95], v[194:197], v[132:135], v[80:95]
	ds_read_b128 v[186:189], v214 offset:54016
	s_waitcnt lgkmcnt(5)
	v_mfma_f32_32x32x16_bf16 v[64:79], v[198:201], v[136:139], v[64:79]
	ds_read_b128 v[190:193], v214 offset:41248
	s_waitcnt lgkmcnt(5)
	v_mfma_f32_32x32x16_bf16 v[80:95], v[202:205], v[136:139], v[80:95]
	ds_read_b128 v[194:197], v214 offset:54048
	s_waitcnt lgkmcnt(5)
	v_mfma_f32_32x32x16_bf16 v[64:79], v[206:209], v[140:143], v[64:79]
	ds_read_b128 v[198:201], v214 offset:41280
	s_waitcnt lgkmcnt(5)
	v_mfma_f32_32x32x16_bf16 v[80:95], v[210:213], v[140:143], v[80:95]
	ds_read_b128 v[202:205], v214 offset:54080
	s_waitcnt lgkmcnt(5)
	v_mfma_f32_32x32x16_bf16 v[64:79], v[182:185], v[144:147], v[64:79]
	ds_read_b128 v[206:209], v214 offset:41312
	s_waitcnt lgkmcnt(5)
	v_mfma_f32_32x32x16_bf16 v[80:95], v[186:189], v[144:147], v[80:95]
	ds_read_b128 v[210:213], v214 offset:54112
	s_waitcnt lgkmcnt(5)
	v_mfma_f32_32x32x16_bf16 v[64:79], v[190:193], v[148:151], v[64:79]
	s_waitcnt lgkmcnt(4)
	v_mfma_f32_32x32x16_bf16 v[80:95], v[194:197], v[148:151], v[80:95]
	s_waitcnt lgkmcnt(3)
	v_mfma_f32_32x32x16_bf16 v[64:79], v[198:201], v[152:155], v[64:79]
	s_waitcnt lgkmcnt(2)
	v_mfma_f32_32x32x16_bf16 v[80:95], v[202:205], v[152:155], v[80:95]
	s_waitcnt lgkmcnt(1)
	v_mfma_f32_32x32x16_bf16 v[64:79], v[206:209], v[156:159], v[64:79]
	s_waitcnt lgkmcnt(0)
	v_mfma_f32_32x32x16_bf16 v[80:95], v[210:213], v[156:159], v[80:95]
	s_branch .Lad_x0_end

; #define LAS __attribute__((address_space(3)))
; DI unsigned pk2(float a, float b) { f32x2 v = {a, b}; bf16v2_t r = __builtin_convertvector(v, bf16v2_t); return __builtin_bit_cast(unsigned, r); }
; DI f32x16 mfma32(bf16x8 a, bf16x8 b, f32x16 c) { return __builtin_amdgcn_mfma_f32_32x32x16_bf16(a, b, c, 0, 0, 0); }
; DI s16x4 trread(LAS unsigned char* p) { return __builtin_amdgcn_ds_read_tr16_b64_v4i16((LAS s16x4*)p); }
; DI bf16x8 cat4(s16x4 lo, s16x4 hi) { return __builtin_shufflevector(lo, hi, 0, 1, 2, 3, 4, 5, 6, 7); }
; template <int DQK, int KA8, int DV, bool BIAS, bool JOINT>
; DI void attn_core(LAS unsigned char* lds, const bf16_t* Qrow, const bf16_t* KpA, int ldkA, const bf16_t* KpB, int ldkB, const bf16_t* Vp, int ldv,
;                   int qb, int wid, int lane, const float* qng  , f32x16 (&O)[DV / 32]) {
;     ...
;             for (int half = 0; half < 2; ++half)
; #pragma unroll
;                 for (int s = 0; s < 2; ++s) {
;                     const f32x16& S = half ? S1 : S0;
;                     u32x4 pw; pw.x = pk2(S[8 * s], S[8 * s + 1]); pw.y = pk2(S[8 * s + 2], S[8 * s + 3]); pw.z = pk2(S[8 * s + 4], S[8 * s + 5]); pw.w = pk2(S[8 * s + 6], S[8 * s + 7]);
;                     const bf16x8 pf = __builtin_bit_cast(bf16x8, pw);
;                     LAS unsigned char* vr = vb + vtr + (32 * half + 16 * s) * VROW;
; #pragma unroll
;                     for (int dt = 0; dt < DV / 32; ++dt) {
;                         const bf16x8 vf = cat4(trread(vr + 64 * dt), trread(vr + 8 * VROW + 64 * dt));
;                         O[dt] = mfma32(vf, pf, O[dt]);
;                     }
.Lad_hn_4:
	ds_read_b64_tr_b16 v[186:187], v215 offset:30784
	ds_read_b64_tr_b16 v[188:189], v215 offset:33344
	s_waitcnt lgkmcnt(12)
	v_mfma_f32_32x32x16_bf16 v[0:15], v[198:201], v[100:103], v[0:15]
	ds_read_b64_tr_b16 v[190:191], v215 offset:30848
	ds_read_b64_tr_b16 v[192:193], v215 offset:33408
	s_waitcnt lgkmcnt(12)
	v_mfma_f32_32x32x16_bf16 v[16:31], v[202:205], v[100:103], v[16:31]
	ds_read_b64_tr_b16 v[194:195], v215 offset:30912
	ds_read_b64_tr_b16 v[196:197], v215 offset:33472
	s_waitcnt lgkmcnt(12)
	v_mfma_f32_32x32x16_bf16 v[32:47], v[206:209], v[100:103], v[32:47]
	ds_read_b64_tr_b16 v[198:199], v215 offset:35840
	ds_read_b64_tr_b16 v[200:201], v215 offset:38400
	s_waitcnt lgkmcnt(12)
	v_mfma_f32_32x32x16_bf16 v[48:63], v[210:213], v[100:103], v[48:63]
	ds_read_b64_tr_b16 v[202:203], v215 offset:35904
	ds_read_b64_tr_b16 v[204:205], v215 offset:38464
	s_waitcnt lgkmcnt(12)
	v_mfma_f32_32x32x16_bf16 v[0:15], v[182:185], v[104:107], v[0:15]
	ds_read_b64_tr_b16 v[206:207], v215 offset:35968
	ds_read_b64_tr_b16 v[208:209], v215 offset:38528
	s_waitcnt lgkmcnt(10)
	v_mfma_f32_32x32x16_bf16 v[16:31], v[186:189], v[104:107], v[16:31]
	ds_read_b64_tr_b16 v[210:211], v215 offset:36032
	ds_read_b64_tr_b16 v[212:213], v215 offset:38592
	s_waitcnt lgkmcnt(10)
	v_mfma_f32_32x32x16_bf16 v[32:47], v[190:193], v[104:107], v[32:47]
	s_waitcnt lgkmcnt(8)
	v_mfma_f32_32x32x16_bf16 v[48:63], v[194:197], v[104:107], v[48:63]
	s_waitcnt lgkmcnt(6)
	v_mfma_f32_32x32x16_bf16 v[0:15], v[198:201], v[108:111], v[0:15]
	s_waitcnt lgkmcnt(4)
	v_mfma_f32_32x32x16_bf16 v[16:31], v[202:205], v[108:111], v[16:31]
	s_waitcnt lgkmcnt(2)
	v_mfma_f32_32x32x16_bf16 v[32:47], v[206:209], v[108:111], v[32:47]
	s_waitcnt lgkmcnt(0)
	v_mfma_f32_32x32x16_bf16 v[48:63], v[210:213], v[108:111], v[48:63]
	s_branch .Lad_x0_end

; #define LAS __attribute__((address_space(3)))
; DI f32x16 mfma32(bf16x8 a, bf16x8 b, f32x16 c) { return __builtin_amdgcn_mfma_f32_32x32x16_bf16(a, b, c, 0, 0, 0); }
; template <int DQK, int KA8, int DV, bool BIAS, bool JOINT>
; DI void attn_core(LAS unsigned char* lds, const bf16_t* Qrow, const bf16_t* KpA, int ldkA, const bf16_t* KpB, int ldkB, const bf16_t* Vp, int ldv,
;                   int qb, int wid, int lane, const float* qng  , f32x16 (&O)[DV / 32]) {
;     ...
; #pragma unroll
;             for (int s = 0; s < DQK / 16; ++s) {
;                 const bf16x8 k0 = *(LAS const bf16x8*)(kb + koff + 32 * s), k1 = *(LAS const bf16x8*)(kb + koff + 32 * KROW + 32 * s);
;                 S0 = mfma32(k0, qf[s], S0); S1 = mfma32(k1, qf[s], S1);
;             }
.Lad_hn_6:
	ds_read_b128 v[186:189], v214 offset:53888
	s_waitcnt lgkmcnt(7)
	v_mfma_f32_32x32x16_bf16 v[64:79], v[198:201], v[120:123], v[64:79]
	ds_read_b128 v[190:193], v214 offset:41120
	s_waitcnt lgkmcnt(7)
	v_mfma_f32_32x32x16_bf16 v[80:95], v[202:205], v[120:123], v[80:95]
	ds_read_b128 v[194:197], v214 offset:53920
	s_waitcnt lgkmcnt(7)
	v_mfma_f32_32x32x16_bf16 v[64:79], v[206:209], v[124:127], v[64:79]
	ds_read_b128 v[198:201], v214 offset:41152
	s_waitcnt lgkmcnt(7)
	v_mfma_f32_32x32x16_bf16 v[80:95], v[210:213], v[124:127], v[80:95]
	ds_read_b128 v[202:205], v214 offset:53952
	s_waitcnt lgkmcnt(7)
	v_mfma_f32_32x32x16_bf16 v[64:79], v[182:185], v[128:131], v[64:79]
	ds_read_b128 v[206:209], v214 offset:41184
	s_waitcnt lgkmcnt(5)
	v_mfma_f32_32x32x16_bf16 v[80:95], v[186:189], v[128:131], v[80:95]
	ds_read_b128 v[210:213], v214 offset:53984
	s_waitcnt lgkmcnt(5)
	v_mfma_f32_32x32x16_bf16 v[64:79], v[190:193], v[132:135], v[64:79]
	ds_read_b128 v[182:185], v214 offset:41216
	s_waitcnt lgkmcnt(5)
	v_mfma_f32_32x32x16_bf16 v[80:95], v[194:197], v[132:135], v[80:95]
	ds_read_b128 v[186:189], v214 offset:54016
	s_waitcnt lgkmcnt(5)
	v_mfma_f32_32x32x16_bf16 v[64:79], v[198:201], v[136:139], v[64:79]
	ds_read_b128 v[190:193], v214 offset:41248
	s_waitcnt lgkmcnt(5)
	v_mfma_f32_32x32x16_bf16 v[80:95], v[202:205], v[136:139], v[80:95]
	ds_read_b128 v[194:197], v214 offset:54048
	s_waitcnt lgkmcnt(5)
	v_mfma_f32_32x32x16_bf16 v[64:79], v[206:209], v[140:143], v[64:79]
	ds_read_b128 v[198:201], v214 offset:41280
	s_waitcnt lgkmcnt(5)
	v_mfma_f32_32x32x16_bf16 v[80:95], v[210:213], v[140:143], v[80:95]
	ds_read_b128 v[202:205], v214 offset:54080
	s_waitcnt lgkmcnt(5)
	v_mfma_f32_32x32x16_bf16 v[64:79], v[182:185], v[144:147], v[64:79]
	ds_read_b128 v[206:209], v214 offset:41312
	s_waitcnt lgkmcnt(5)
	v_mfma_f32_32x32x16_bf16 v[80:95], v[186:189], v[144:147], v[80:95]
	ds_read_b128 v[210:213], v214 offset:54112
	s_waitcnt lgkmcnt(5)
	v_mfma_f32_32x32x16_bf16 v[64:79], v[190:193], v[148:151], v[64:79]
	s_waitcnt lgkmcnt(4)
	v_mfma_f32_32x32x16_bf16 v[80:95], v[194:197], v[148:151], v[80:95]
	s_waitcnt lgkmcnt(3)
	v_mfma_f32_32x32x16_bf16 v[64:79], v[198:201], v[152:155], v[64:79]
	s_waitcnt lgkmcnt(2)
	v_mfma_f32_32x32x16_bf16 v[80:95], v[202:205], v[152:155], v[80:95]
	s_waitcnt lgkmcnt(1)
	v_mfma_f32_32x32x16_bf16 v[64:79], v[206:209], v[156:159], v[64:79]
	s_waitcnt lgkmcnt(0)
	v_mfma_f32_32x32x16_bf16 v[80:95], v[210:213], v[156:159], v[80:95]
	s_branch .Lad_x0_end

; template <int DQK, int KA8, int DV, bool BIAS, bool JOINT>
; DI void attn_core(LAS unsigned char* lds, const bf16_t* Qrow, const bf16_t* KpA, int ldkA, const bf16_t* KpB, int ldkB, const bf16_t* Vp, int ldv,
;                   int qb, int wid, int lane, const float* qng  , f32x16 (&O)[DV / 32]) {
;     ...
;             if (mnz) {
; #pragma unroll
;                 for (int i = 0; i < 16; ++i) { S0[i] -= m; S1[i] -= m; }
;             }
.Lad_hn_8:
.Lad_x0_end:
	s_waitcnt lgkmcnt(0)
	s_barrier
	s_cmp_gt_u32 s24, s25
	s_cbranch_scc1 .Lad_y0_end
	s_nop 15
	s_cmp_eq_u32 s40, 0
	s_cbranch_scc1 .Lad_y0_nosubm
	v_sub_f32_e32 v64, v64, v224
	v_sub_f32_e32 v65, v65, v224
	v_sub_f32_e32 v66, v66, v224
	v_sub_f32_e32 v67, v67, v224
	v_sub_f32_e32 v68, v68, v224
	v_sub_f32_e32 v69, v69, v224
	v_sub_f32_e32 v70, v70, v224
	v_sub_f32_e32 v71, v71, v224
	v_sub_f32_e32 v72, v72, v224
	v_sub_f32_e32 v73, v73, v224
	v_sub_f32_e32 v74, v74, v224
	v_sub_f32_e32 v75, v75, v224
	v_sub_f32_e32 v76, v76, v224
	v_sub_f32_e32 v77, v77, v224
	v_sub_f32_e32 v78, v78, v224
	v_sub_f32_e32 v79, v79, v224
	v_sub_f32_e32 v80, v80, v224
	v_sub_f32_e32 v81, v81, v224
	v_sub_f32_e32 v82, v82, v224
	v_sub_f32_e32 v83, v83, v224
	v_sub_f32_e32 v84, v84, v224
	v_sub_f32_e32 v85, v85, v224
	v_sub_f32_e32 v86, v86, v224
	v_sub_f32_e32 v87, v87, v224
	v_sub_f32_e32 v88, v88, v224
	v_sub_f32_e32 v89, v89, v224
	v_sub_f32_e32 v90, v90, v224
	v_sub_f32_e32 v91, v91, v224
	v_sub_f32_e32 v92, v92, v224
	v_sub_f32_e32 v93, v93, v224
	v_sub_f32_e32 v94, v94, v224
	v_sub_f32_e32 v95, v95, v224

; template <int DQK, int KA8, int DV, bool BIAS, bool JOINT>
; DI void attn_core(LAS unsigned char* lds, const bf16_t* Qrow, const bf16_t* KpA, int ldkA, const bf16_t* KpB, int ldkB, const bf16_t* Vp, int ldv,
;                   int qb, int wid, int lane, const float* qng  , f32x16 (&O)[DV / 32]) {
;     ...
;     auto gload = [&](int kt) {
; #pragma unroll
;         for (int i = 0; i < NL; ++i) { const int c = tid + i * 512;
;             if (i * 512 < NKC) { const int row = c / KC, cc = c % KC;
;                 const bf16_t* src = (cc < KA8) ? KpA + (size_t)(kt * 64 + row) * ldkA + cc * 8 : KpB + (size_t)(kt * 64 + row) * ldkB + (cc - KA8) * 8;
;                 stg[i] = *(const u32x4*)src; }
;             else { const int c2 = c - NKC, row = c2 / VC, cc = c2 % VC; stg[i] = *(const u32x4*)(Vp + (size_t)(kt * 64 + row) * ldv + cc * 8); } }
;     };
;     auto lstore = [&](int buf) {
; #pragma unroll
;         for (int i = 0; i < NL; ++i) { const int c = tid + i * 512;
;             if (i * 512 < NKC) { const int row = c / KC, cc = c % KC; *(LAS u32x4*)(lds + buf * STG + row * KROW + cc * 16) = stg[i]; }
;             else { const int c2 = c - NKC, row = c2 / VC, cc = c2 % VC; *(LAS u32x4*)(lds + buf * STG + 64 * KROW + row * VROW + cc * 16) = stg[i]; } }
;     };
;     gload(0); lstore(0); __syncthreads();
;     for (int kt = 0; kt < nkt; ++kt) {
;         if (kt + 1 < nkt) gload(kt + 1);
;         if (JOINT && kt <= myc) {
;             LAS unsigned char* kb = lds + (kt & 1) * STG; LAS unsigned char* vb = kb + 64 * KROW;
;             const bool far = (kt * 64 + 63 - q0w <= -91);
;             f32x16 S0, S1;
; #pragma unroll
;             for (int i = 0; i < 16; ++i) { S0[i] = 0.f; S1[i] = 0.f; }
; #pragma unroll
;             for (int s = 0; s < DQK / 16; ++s) {
;                 const bf16x8 k0 = *(LAS const bf16x8*)(kb + koff + 32 * s), k1 = *(LAS const bf16x8*)(kb + koff + 32 * KROW + 32 * s);
;                 S0 = mfma32(k0, qf[s], S0); S1 = mfma32(k1, qf[s], S1);
;             }
;     ...
;             for (int half = 0; half < 2; ++half)
; #pragma unroll
;                 for (int s = 0; s < 2; ++s) {
;                     const f32x16& S = half ? S1 : S0;
;                     u32x4 pw; pw.x = pk2(S[8 * s], S[8 * s + 1]); pw.y = pk2(S[8 * s + 2], S[8 * s + 3]); pw.z = pk2(S[8 * s + 4], S[8 * s + 5]); pw.w = pk2(S[8 * s + 6], S[8 * s + 7]);
.Lad_hv_9:
	ds_write_b128 v218, v[172:175] offset:20480
	ds_write_b128 v218, v[176:179] offset:30720
	s_cbranch_scc0 .Lad_hn_10
	global_load_dwordx4 v[172:175], v222, s[34:35]
	global_load_dwordx4 v[176:179], v223, s[34:35]
	s_add_u32 s34, s34, 0xe0000
	s_addc_u32 s35, s35, 0
	s_add_i32 s58, s59, 2
	s_cmp_lt_u32 s58, s17
	s_cbranch_scc0 .Lad_hn_10
	global_load_dwordx4 v[160:163], v219, s[30:31]
	global_load_dwordx4 v[164:167], v220, s[30:31]
	global_load_dwordx4 v[168:171], v221, s[36:37]
	s_add_u32 s30, s30, 0xe0000
	s_addc_u32 s31, s31, 0
	s_add_u32 s36, s36, 0x22000
	s_addc_u32 s37, s37, 0
.Lad_hn_10:
	ds_read_b64_tr_b16 v[186:187], v215 offset:10304
	ds_read_b64_tr_b16 v[188:189], v215 offset:12864
	s_waitcnt lgkmcnt(12)
	v_mfma_f32_32x32x16_bf16 v[0:15], v[198:201], v[100:103], v[0:15]
	ds_read_b64_tr_b16 v[190:191], v215 offset:10368
	ds_read_b64_tr_b16 v[192:193], v215 offset:12928
	s_waitcnt lgkmcnt(12)
	v_mfma_f32_32x32x16_bf16 v[16:31], v[202:205], v[100:103], v[16:31]
	ds_read_b64_tr_b16 v[194:195], v215 offset:10432
	ds_read_b64_tr_b16 v[196:197], v215 offset:12992
	s_waitcnt lgkmcnt(12)
	v_mfma_f32_32x32x16_bf16 v[32:47], v[206:209], v[100:103], v[32:47]
	ds_read_b64_tr_b16 v[198:199], v215 offset:15360
	ds_read_b64_tr_b16 v[200:201], v215 offset:17920
	s_waitcnt lgkmcnt(12)
	v_mfma_f32_32x32x16_bf16 v[48:63], v[210:213], v[100:103], v[48:63]
	ds_read_b64_tr_b16 v[202:203], v215 offset:15424
	ds_read_b64_tr_b16 v[204:205], v215 offset:17984
	s_waitcnt lgkmcnt(12)
	v_mfma_f32_32x32x16_bf16 v[0:15], v[182:185], v[104:107], v[0:15]
	ds_read_b64_tr_b16 v[206:207], v215 offset:15488
	ds_read_b64_tr_b16 v[208:209], v215 offset:18048
	s_waitcnt lgkmcnt(10)
	v_mfma_f32_32x32x16_bf16 v[16:31], v[186:189], v[104:107], v[16:31]
	ds_read_b64_tr_b16 v[210:211], v215 offset:15552
	ds_read_b64_tr_b16 v[212:213], v215 offset:18112
	s_waitcnt lgkmcnt(10)
	v_mfma_f32_32x32x16_bf16 v[32:47], v[190:193], v[104:107], v[32:47]
	ds_read_b128 v[182:185], v252 offset:0
	s_waitcnt lgkmcnt(9)
	v_mfma_f32_32x32x16_bf16 v[48:63], v[194:197], v[104:107], v[48:63]
	ds_read_b128 v[186:189], v252 offset:12800
	s_waitcnt lgkmcnt(8)
	v_mfma_f32_32x32x16_bf16 v[0:15], v[198:201], v[108:111], v[0:15]
	ds_read_b128 v[190:193], v252 offset:32
	s_waitcnt lgkmcnt(7)
	v_mfma_f32_32x32x16_bf16 v[16:31], v[202:205], v[108:111], v[16:31]
	ds_read_b128 v[194:197], v252 offset:12832
	s_waitcnt lgkmcnt(6)
	v_mfma_f32_32x32x16_bf16 v[32:47], v[206:209], v[108:111], v[32:47]
	ds_read_b128 v[198:201], v252 offset:64
	s_waitcnt lgkmcnt(5)
	v_mfma_f32_32x32x16_bf16 v[48:63], v[210:213], v[108:111], v[48:63]
	ds_read_b128 v[202:205], v252 offset:12864
	s_waitcnt lgkmcnt(5)
	v_mfma_f32_32x32x16_bf16 v[64:79], v[182:185], v[112:115], 0
	ds_read_b128 v[206:209], v252 offset:96
	s_waitcnt lgkmcnt(5)
	v_mfma_f32_32x32x16_bf16 v[80:95], v[186:189], v[112:115], 0
	ds_read_b128 v[210:213], v252 offset:12896
	s_waitcnt lgkmcnt(5)
	v_mfma_f32_32x32x16_bf16 v[64:79], v[190:193], v[116:119], v[64:79]
	ds_read_b128 v[182:185], v252 offset:128
	s_waitcnt lgkmcnt(5)
	v_mfma_f32_32x32x16_bf16 v[80:95], v[194:197], v[116:119], v[80:95]
	ds_read_b128 v[186:189], v252 offset:12928
	s_waitcnt lgkmcnt(5)
	v_mfma_f32_32x32x16_bf16 v[64:79], v[198:201], v[120:123], v[64:79]
	ds_read_b128 v[190:193], v252 offset:160
	s_waitcnt lgkmcnt(5)
	v_mfma_f32_32x32x16_bf16 v[80:95], v[202:205], v[120:123], v[80:95]
	ds_read_b128 v[194:197], v252 offset:12960
	s_waitcnt lgkmcnt(5)
	v_mfma_f32_32x32x16_bf16 v[64:79], v[206:209], v[124:127], v[64:79]
	ds_read_b128 v[198:201], v252 offset:192
	s_waitcnt lgkmcnt(5)
	v_mfma_f32_32x32x16_bf16 v[80:95], v[210:213], v[124:127], v[80:95]
	ds_read_b128 v[202:205], v252 offset:12992
	s_waitcnt lgkmcnt(5)
	v_mfma_f32_32x32x16_bf16 v[64:79], v[182:185], v[128:131], v[64:79]
	ds_read_b128 v[206:209], v252 offset:224
	s_waitcnt lgkmcnt(5)
	v_mfma_f32_32x32x16_bf16 v[80:95], v[186:189], v[128:131], v[80:95]
	ds_read_b128 v[210:213], v252 offset:13024
	s_waitcnt lgkmcnt(5)
	v_mfma_f32_32x32x16_bf16 v[64:79], v[190:193], v[132:135], v[64:79]
	ds_read_b128 v[182:185], v252 offset:256
	s_waitcnt lgkmcnt(5)
	v_mfma_f32_32x32x16_bf16 v[80:95], v[194:197], v[132:135], v[80:95]
	ds_read_b128 v[186:189], v252 offset:13056
	s_waitcnt lgkmcnt(5)
	v_mfma_f32_32x32x16_bf16 v[64:79], v[198:201], v[136:139], v[64:79]
	ds_read_b128 v[190:193], v252 offset:288
	s_waitcnt lgkmcnt(5)
	v_mfma_f32_32x32x16_bf16 v[80:95], v[202:205], v[136:139], v[80:95]
	ds_read_b128 v[194:197], v252 offset:13088
	s_waitcnt lgkmcnt(5)
	v_mfma_f32_32x32x16_bf16 v[64:79], v[206:209], v[140:143], v[64:79]
	ds_read_b128 v[198:201], v252 offset:320
	s_waitcnt lgkmcnt(5)
	v_mfma_f32_32x32x16_bf16 v[80:95], v[210:213], v[140:143], v[80:95]
	ds_read_b128 v[202:205], v252 offset:13120
	s_waitcnt lgkmcnt(5)
	v_mfma_f32_32x32x16_bf16 v[64:79], v[182:185], v[144:147], v[64:79]
	ds_read_b128 v[206:209], v252 offset:352
	s_waitcnt lgkmcnt(5)
	v_mfma_f32_32x32x16_bf16 v[80:95], v[186:189], v[144:147], v[80:95]
	ds_read_b128 v[210:213], v252 offset:13152
	s_waitcnt lgkmcnt(5)
	v_mfma_f32_32x32x16_bf16 v[64:79], v[190:193], v[148:151], v[64:79]
	s_waitcnt lgkmcnt(4)
	v_mfma_f32_32x32x16_bf16 v[80:95], v[194:197], v[148:151], v[80:95]
	s_waitcnt lgkmcnt(3)
	v_mfma_f32_32x32x16_bf16 v[64:79], v[198:201], v[152:155], v[64:79]
	s_waitcnt lgkmcnt(2)
	v_mfma_f32_32x32x16_bf16 v[80:95], v[202:205], v[152:155], v[80:95]
	s_waitcnt lgkmcnt(1)
	v_mfma_f32_32x32x16_bf16 v[64:79], v[206:209], v[156:159], v[64:79]
	s_waitcnt lgkmcnt(0)
	v_mfma_f32_32x32x16_bf16 v[80:95], v[210:213], v[156:159], v[80:95]
	s_branch .Lad_x1_end

; #define LAS __attribute__((address_space(3)))
; DI unsigned pk2(float a, float b) { f32x2 v = {a, b}; bf16v2_t r = __builtin_convertvector(v, bf16v2_t); return __builtin_bit_cast(unsigned, r); }
; DI f32x16 mfma32(bf16x8 a, bf16x8 b, f32x16 c) { return __builtin_amdgcn_mfma_f32_32x32x16_bf16(a, b, c, 0, 0, 0); }
; DI s16x4 trread(LAS unsigned char* p) { return __builtin_amdgcn_ds_read_tr16_b64_v4i16((LAS s16x4*)p); }
; DI bf16x8 cat4(s16x4 lo, s16x4 hi) { return __builtin_shufflevector(lo, hi, 0, 1, 2, 3, 4, 5, 6, 7); }
; template <int DQK, int KA8, int DV, bool BIAS, bool JOINT>
; DI void attn_core(LAS unsigned char* lds, const bf16_t* Qrow, const bf16_t* KpA, int ldkA, const bf16_t* KpB, int ldkB, const bf16_t* Vp, int ldv,
;                   int qb, int wid, int lane, const float* qng  , f32x16 (&O)[DV / 32]) {
;     ...
;             for (int half = 0; half < 2; ++half)
; #pragma unroll
;                 for (int s = 0; s < 2; ++s) {
;                     const f32x16& S = half ? S1 : S0;
;                     u32x4 pw; pw.x = pk2(S[8 * s], S[8 * s + 1]); pw.y = pk2(S[8 * s + 2], S[8 * s + 3]); pw.z = pk2(S[8 * s + 4], S[8 * s + 5]); pw.w = pk2(S[8 * s + 6], S[8 * s + 7]);
;                     const bf16x8 pf = __builtin_bit_cast(bf16x8, pw);
;                     LAS unsigned char* vr = vb + vtr + (32 * half + 16 * s) * VROW;
; #pragma unroll
;                     for (int dt = 0; dt < DV / 32; ++dt) {
;                         const bf16x8 vf = cat4(trread(vr + 64 * dt), trread(vr + 8 * VROW + 64 * dt));
;                         O[dt] = mfma32(vf, pf, O[dt]);
;                     }
.Lad_hn_12:
	ds_read_b64_tr_b16 v[186:187], v215 offset:10304
	ds_read_b64_tr_b16 v[188:189], v215 offset:12864
	s_waitcnt lgkmcnt(12)
	v_mfma_f32_32x32x16_bf16 v[0:15], v[198:201], v[100:103], v[0:15]
	ds_read_b64_tr_b16 v[190:191], v215 offset:10368
	ds_read_b64_tr_b16 v[192:193], v215 offset:12928
	s_waitcnt lgkmcnt(12)
	v_mfma_f32_32x32x16_bf16 v[16:31], v[202:205], v[100:103], v[16:31]
	ds_read_b64_tr_b16 v[194:195], v215 offset:10432
	ds_read_b64_tr_b16 v[196:197], v215 offset:12992
	s_waitcnt lgkmcnt(12)
	v_mfma_f32_32x32x16_bf16 v[32:47], v[206:209], v[100:103], v[32:47]
	ds_read_b64_tr_b16 v[198:199], v215 offset:15360
	ds_read_b64_tr_b16 v[200:201], v215 offset:17920
	s_waitcnt lgkmcnt(12)
	v_mfma_f32_32x32x16_bf16 v[48:63], v[210:213], v[100:103], v[48:63]
	ds_read_b64_tr_b16 v[202:203], v215 offset:15424
	ds_read_b64_tr_b16 v[204:205], v215 offset:17984
	s_waitcnt lgkmcnt(12)
	v_mfma_f32_32x32x16_bf16 v[0:15], v[182:185], v[104:107], v[0:15]
	ds_read_b64_tr_b16 v[206:207], v215 offset:15488
	ds_read_b64_tr_b16 v[208:209], v215 offset:18048
	s_waitcnt lgkmcnt(10)
	v_mfma_f32_32x32x16_bf16 v[16:31], v[186:189], v[104:107], v[16:31]
	ds_read_b64_tr_b16 v[210:211], v215 offset:15552
	ds_read_b64_tr_b16 v[212:213], v215 offset:18112
	s_waitcnt lgkmcnt(10)
	v_mfma_f32_32x32x16_bf16 v[32:47], v[190:193], v[104:107], v[32:47]
	s_waitcnt lgkmcnt(8)
	v_mfma_f32_32x32x16_bf16 v[48:63], v[194:197], v[104:107], v[48:63]
	s_waitcnt lgkmcnt(6)
	v_mfma_f32_32x32x16_bf16 v[0:15], v[198:201], v[108:111], v[0:15]
	s_waitcnt lgkmcnt(4)
	v_mfma_f32_32x32x16_bf16 v[16:31], v[202:205], v[108:111], v[16:31]
	s_waitcnt lgkmcnt(2)
	v_mfma_f32_32x32x16_bf16 v[32:47], v[206:209], v[108:111], v[32:47]
	s_waitcnt lgkmcnt(0)
	v_mfma_f32_32x32x16_bf16 v[48:63], v[210:213], v[108:111], v[48:63]
	s_branch .Lad_x1_end

; template <int DQK, int KA8, int DV, bool BIAS, bool JOINT>
; DI void attn_core(LAS unsigned char* lds, const bf16_t* Qrow, const bf16_t* KpA, int ldkA, const bf16_t* KpB, int ldkB, const bf16_t* Vp, int ldv,
;                   int qb, int wid, int lane, const float* qng  , f32x16 (&O)[DV / 32]) {
;     ...
;             if (mnz) {
; #pragma unroll
;                 for (int i = 0; i < 16; ++i) { S0[i] -= m; S1[i] -= m; }
;             }
.Lad_hn_14:
.Lad_x1_end:
	s_waitcnt lgkmcnt(0)
	s_barrier
	s_cmp_gt_u32 s59, s25
	s_cbranch_scc1 .Lad_y1_end
	s_nop 15
	s_cmp_eq_u32 s40, 0
	s_cbranch_scc1 .Lad_y1_nosubm
	v_sub_f32_e32 v64, v64, v224
	v_sub_f32_e32 v65, v65, v224
	v_sub_f32_e32 v66, v66, v224
	v_sub_f32_e32 v67, v67, v224
	v_sub_f32_e32 v68, v68, v224
	v_sub_f32_e32 v69, v69, v224
	v_sub_f32_e32 v70, v70, v224
	v_sub_f32_e32 v71, v71, v224
	v_sub_f32_e32 v72, v72, v224
	v_sub_f32_e32 v73, v73, v224
	v_sub_f32_e32 v74, v74, v224
	v_sub_f32_e32 v75, v75, v224
	v_sub_f32_e32 v76, v76, v224
	v_sub_f32_e32 v77, v77, v224
	v_sub_f32_e32 v78, v78, v224
	v_sub_f32_e32 v79, v79, v224
	v_sub_f32_e32 v80, v80, v224
	v_sub_f32_e32 v81, v81, v224
	v_sub_f32_e32 v82, v82, v224
	v_sub_f32_e32 v83, v83, v224
	v_sub_f32_e32 v84, v84, v224
	v_sub_f32_e32 v85, v85, v224
	v_sub_f32_e32 v86, v86, v224
	v_sub_f32_e32 v87, v87, v224
	v_sub_f32_e32 v88, v88, v224
	v_sub_f32_e32 v89, v89, v224
	v_sub_f32_e32 v90, v90, v224
	v_sub_f32_e32 v91, v91, v224
	v_sub_f32_e32 v92, v92, v224
	v_sub_f32_e32 v93, v93, v224
	v_sub_f32_e32 v94, v94, v224
	v_sub_f32_e32 v95, v95, v224
